# residual-GEMM epilogues (out-proj, down-proj, both layers): 16 L2-warming touch loads of the residual rows issued before the serialized read-modify-write chain
# baseline (speedup 1.0000x reference)
;     __device__ __forceinline__ void operator()(f32x4 (&acc)[2][2][4][2], const Unit& u, int wr, int wc, int fr, int fq) const {
;         const int row0 = u.pm * BM + wr * 64 + fr, col0 = u.pn * BM + wc * 32 + 8 * fq;
;         const int r = u.pm < 32 ? (u.pm >> 3) : 4;
;         const float* gt = mod + (size_t)r * MODW + gate_off + col0;
;         f32x4 gv[2][2];
; #pragma unroll
;         for (int bj = 0; bj < 2; ++bj)
; #pragma unroll
;             for (int n = 0; n < 2; ++n) gv[bj][n] = *(const f32x4*)(gt + bj * HALF + 4 * n);
;         if (u.ks >= 0) {
;             float* pb = PART + ((size_t)u.ks * TC + (size_t)(row0 - TL)) * DM + col0;
; #pragma unroll
;             for (int ai = 0; ai < 2; ++ai)
; #pragma unroll
;                 for (int m = 0; m < 4; ++m)
; #pragma unroll
;                     for (int bj = 0; bj < 2; ++bj) { float* q = pb + (size_t)(ai * HALF + m * 16) * DM + bj * HALF;
;                         *(f32x4*)q = gv[bj][0] * acc[ai][bj][m][0]; *(f32x4*)(q + 4) = gv[bj][1] * acc[ai][bj][m][1]; }
;             return;
;         }
; #pragma unroll
;         for (int ai = 0; ai < 2; ++ai)
; #pragma unroll
;             for (int m = 0; m < 4; ++m) { const size_t ro = (size_t)(row0 + ai * HALF + m * 16) * DM + col0;
; #pragma unroll
;                 for (int bj = 0; bj < 2; ++bj) { f32x4 x0, x1;
;                     if (Xf32 != nullptr) { x0 = *(const f32x4*)(Xf32 + ro + bj * HALF); x1 = *(const f32x4*)(Xf32 + ro + bj * HALF + 4); }
.LBB0_671:
	v_lshl_or_b32 v162, s50, 8, v172
	s_lshl_b64 s[50:51], s[52:53], 2
	s_add_u32 s50, s2, s50
	s_addc_u32 s51, s3, s51
	v_ashrrev_i32_e32 v163, 31, v162
	v_lshl_add_u64 v[128:129], v[162:163], 2, s[50:51]
	s_mov_b64 s[50:51], 0x12104000
	s_mov_b32 s9, 0x12104000
	v_lshl_add_u64 v[132:133], v[128:129], 0, s[50:51]
	v_add_co_u32_e32 v128, vcc, s9, v128
	v_lshl_add_u32 v164, s8, 8, v170
	s_nop 0
	v_addc_co_u32_e32 v129, vcc, 0, v129, vcc
	global_load_dwordx4 v[140:143], v[128:129], off
	s_nop 0
	global_load_dwordx4 v[128:131], v[132:133], off offset:528
	global_load_dwordx4 v[136:139], v[132:133], off offset:16
	s_nop 0
	global_load_dwordx4 v[132:135], v[132:133], off offset:512
	s_mov_b64 s[8:9], -1
	s_cmp_gt_i32 s28, -1
	v_ashrrev_i32_e32 v165, 31, v164
	s_cbranch_scc1 .LBB0_722
	v_lshlrev_b64 v[144:145], 11, v[164:165]
	v_lshl_add_u64 v[166:167], v[144:145], 0, v[162:163]
	s_and_b64 vcc, exec, s[26:27]
	v_lshl_add_u64 v[168:169], v[166:167], 2, s[14:15]
	s_cbranch_vccz .LBB0_726
	global_load_dword v244, v[168:169], off
	global_load_dword v244, v[168:169], off offset:512
	v_mov_b32_e32 v240, 0x20000
	v_mov_b32_e32 v241, 0
	v_lshl_add_u64 v[242:243], v[168:169], 0, v[240:241]
	global_load_dword v244, v[242:243], off
	global_load_dword v244, v[242:243], off offset:512
	v_lshl_add_u64 v[242:243], v[242:243], 0, v[240:241]
	global_load_dword v244, v[242:243], off
	global_load_dword v244, v[242:243], off offset:512
	v_lshl_add_u64 v[242:243], v[242:243], 0, v[240:241]
	global_load_dword v244, v[242:243], off
	global_load_dword v244, v[242:243], off offset:512
	v_mov_b32_e32 v240, 0xa0000
	v_lshl_add_u64 v[242:243], v[242:243], 0, v[240:241]
	global_load_dword v244, v[242:243], off
	global_load_dword v244, v[242:243], off offset:512
	v_mov_b32_e32 v240, 0x20000
	v_lshl_add_u64 v[242:243], v[242:243], 0, v[240:241]
	global_load_dword v244, v[242:243], off
	global_load_dword v244, v[242:243], off offset:512
	v_lshl_add_u64 v[242:243], v[242:243], 0, v[240:241]
	global_load_dword v244, v[242:243], off
	global_load_dword v244, v[242:243], off offset:512
	v_lshl_add_u64 v[242:243], v[242:243], 0, v[240:241]
	global_load_dword v244, v[242:243], off
	global_load_dword v244, v[242:243], off offset:512
	global_load_dwordx4 v[144:147], v[168:169], off offset:16
	global_load_dwordx4 v[148:151], v[168:169], off
	v_lshl_add_u64 v[166:167], v[166:167], 1, s[20:21]
	s_cbranch_execnz .LBB0_675

; __device__ __forceinline__ unsigned cvt_pk_bf16(float lo, float hi) { unsigned r; asm volatile("v_cvt_pk_bf16_f32 %0, %1, %2" : "=v"(r) : "v"(lo), "v"(hi)); return r; }
; __device__ __forceinline__ float lo_f(unsigned w) { return __uint_as_float(w << 16); }
; __device__ __forceinline__ float hi_f(unsigned w) { return __uint_as_float(w & 0xffff0000u); }
;     __device__ __forceinline__ void operator()(f32x4 (&acc)[2][2][4][2], const Unit& u, int wr, int wc, int fr, int fq) const {
;     ...
; #pragma unroll
;         for (int ai = 0; ai < 2; ++ai)
; #pragma unroll
;             for (int m = 0; m < 4; ++m) { const size_t ro = (size_t)(row0 + ai * HALF + m * 16) * DM + col0;
; #pragma unroll
;                 for (int bj = 0; bj < 2; ++bj) { f32x4 x0, x1;
;                     if (Xf32 != nullptr) { x0 = *(const f32x4*)(Xf32 + ro + bj * HALF); x1 = *(const f32x4*)(Xf32 + ro + bj * HALF + 4); }
;                     else { const u32x4 xb = *(const u32x4*)(X + ro + bj * HALF);
;                         x0 = (f32x4){lo_f(xb.x), hi_f(xb.x), lo_f(xb.y), hi_f(xb.y)}; x1 = (f32x4){lo_f(xb.z), hi_f(xb.z), lo_f(xb.w), hi_f(xb.w)}; }
;                     x0 += gv[bj][0] * acc[ai][bj][m][0]; x1 += gv[bj][1] * acc[ai][bj][m][1];
;                     u32x4 w; w.x = cvt_pk_bf16(x0[0], x0[1]); w.y = cvt_pk_bf16(x0[2], x0[3]); w.z = cvt_pk_bf16(x1[0], x1[1]); w.w = cvt_pk_bf16(x1[2], x1[3]);
;                     *(u32x4*)(X + ro + bj * HALF) = w; } }
.LBB0_1123:
	s_lshl_b64 s[34:35], s[34:35], 2
	v_lshl_or_b32 v158, s93, 8, v168
	s_add_u32 s34, s2, s34
	s_addc_u32 s35, s3, s35
	v_ashrrev_i32_e32 v159, 31, v158
	v_lshl_add_u64 v[128:129], v[158:159], 2, s[34:35]
	s_mov_b64 s[34:35], 0x1210a000
	v_lshl_add_u64 v[132:133], v[128:129], 0, s[34:35]
	s_mov_b32 s34, 0x1210a000
	v_add_co_u32_e32 v128, vcc, s34, v128
	v_lshl_add_u32 v160, s92, 8, v166
	s_nop 0
	v_addc_co_u32_e32 v129, vcc, 0, v129, vcc
	global_load_dwordx4 v[140:143], v[128:129], off
	s_nop 0
	global_load_dwordx4 v[128:131], v[132:133], off offset:528
	global_load_dwordx4 v[136:139], v[132:133], off offset:16
	s_nop 0
	global_load_dwordx4 v[132:135], v[132:133], off offset:512
	s_mov_b64 s[34:35], -1
	s_cmp_gt_i32 s6, -1
	v_ashrrev_i32_e32 v161, 31, v160
	s_cbranch_scc1 .LBB0_1126
	v_lshlrev_b64 v[162:163], 12, v[160:161]
	v_lshl_add_u64 v[162:163], s[10:11], 0, v[162:163]
	v_lshlrev_b64 v[164:165], 1, v[158:159]
	v_lshl_add_u64 v[162:163], v[162:163], 0, v[164:165]
	global_load_dwordx4 v[172:175], v[162:163], off
	global_load_dword v244, v[162:163], off
	global_load_dword v244, v[162:163], off offset:256
	v_mov_b32_e32 v240, 0x10000
	v_mov_b32_e32 v241, 0
	v_lshl_add_u64 v[242:243], v[162:163], 0, v[240:241]
	global_load_dword v244, v[242:243], off
	global_load_dword v244, v[242:243], off offset:256
	v_lshl_add_u64 v[242:243], v[242:243], 0, v[240:241]
	global_load_dword v244, v[242:243], off
	global_load_dword v244, v[242:243], off offset:256
	v_lshl_add_u64 v[242:243], v[242:243], 0, v[240:241]
	global_load_dword v244, v[242:243], off
	global_load_dword v244, v[242:243], off offset:256
	v_mov_b32_e32 v240, 0x50000
	v_lshl_add_u64 v[242:243], v[242:243], 0, v[240:241]
	global_load_dword v244, v[242:243], off
	global_load_dword v244, v[242:243], off offset:256
	v_mov_b32_e32 v240, 0x10000
	v_lshl_add_u64 v[242:243], v[242:243], 0, v[240:241]
	global_load_dword v244, v[242:243], off
	global_load_dword v244, v[242:243], off offset:256
	v_lshl_add_u64 v[242:243], v[242:243], 0, v[240:241]
	global_load_dword v244, v[242:243], off
	global_load_dword v244, v[242:243], off offset:256
	v_lshl_add_u64 v[242:243], v[242:243], 0, v[240:241]
	global_load_dword v244, v[242:243], off
	global_load_dword v244, v[242:243], off offset:256
	v_or_b32_e32 v182, 32, v160
	v_ashrrev_i32_e32 v183, 31, v182
	v_lshlrev_b64 v[182:183], 12, v[182:183]
	v_lshl_add_u64 v[182:183], s[10:11], 0, v[182:183]
	v_lshl_add_u64 v[182:183], v[182:183], 0, v[164:165]
	s_waitcnt vmcnt(0)
	v_lshlrev_b32_e32 v176, 16, v172
	v_and_b32_e32 v177, 0xffff0000, v172
	v_lshlrev_b32_e32 v172, 16, v173
	v_and_b32_e32 v173, 0xffff0000, v173
	v_lshlrev_b32_e32 v178, 16, v174
	v_and_b32_e32 v179, 0xffff0000, v174
	v_lshlrev_b32_e32 v174, 16, v175
	v_and_b32_e32 v175, 0xffff0000, v175
	v_pk_fma_f32 v[180:181], v[126:127], v[142:143], v[172:173]
	v_pk_fma_f32 v[172:173], v[124:125], v[140:141], v[176:177]
	v_pk_fma_f32 v[176:177], v[122:123], v[138:139], v[174:175]
	v_pk_fma_f32 v[174:175], v[120:121], v[136:137], v[178:179]
	v_cvt_pk_bf16_f32 v172, v172, v173
	v_cvt_pk_bf16_f32 v173, v180, v181
	v_or_b32_e32 v180, 16, v160
	v_cvt_pk_bf16_f32 v174, v174, v175
	v_cvt_pk_bf16_f32 v175, v176, v177
	global_load_dwordx4 v[176:179], v[162:163], off offset:256
	v_ashrrev_i32_e32 v181, 31, v180
	v_lshlrev_b64 v[180:181], 12, v[180:181]
	v_lshl_add_u64 v[180:181], s[10:11], 0, v[180:181]
	global_store_dwordx4 v[162:163], v[172:175], off
	v_lshl_add_u64 v[180:181], v[180:181], 0, v[164:165]
	s_waitcnt vmcnt(1)
	v_lshlrev_b32_e32 v172, 16, v176
	v_and_b32_e32 v173, 0xffff0000, v176
	v_lshlrev_b32_e32 v174, 16, v177
	v_and_b32_e32 v175, 0xffff0000, v177
	v_lshlrev_b32_e32 v176, 16, v178
	v_and_b32_e32 v177, 0xffff0000, v178
	v_lshlrev_b32_e32 v178, 16, v179
	v_and_b32_e32 v179, 0xffff0000, v179
	v_pk_fma_f32 v[174:175], v[114:115], v[134:135], v[174:175]
	v_pk_fma_f32 v[172:173], v[112:113], v[132:133], v[172:173]
	v_pk_fma_f32 v[178:179], v[106:107], v[130:131], v[178:179]
	v_pk_fma_f32 v[176:177], v[104:105], v[128:129], v[176:177]
	v_cvt_pk_bf16_f32 v172, v172, v173
	v_cvt_pk_bf16_f32 v173, v174, v175
	s_nop 0
	v_cvt_pk_bf16_f32 v174, v176, v177
	v_cvt_pk_bf16_f32 v175, v178, v179
	global_load_dwordx4 v[176:179], v[180:181], off
	s_nop 0
	global_store_dwordx4 v[162:163], v[172:175], off offset:256
	s_waitcnt vmcnt(1)
	s_nop 0
	v_lshlrev_b32_e32 v172, 16, v176
	v_and_b32_e32 v173, 0xffff0000, v176
	v_lshlrev_b32_e32 v174, 16, v177
	v_and_b32_e32 v175, 0xffff0000, v177
	v_lshlrev_b32_e32 v176, 16, v178
	v_and_b32_e32 v177, 0xffff0000, v178
	v_lshlrev_b32_e32 v178, 16, v179
	v_and_b32_e32 v179, 0xffff0000, v179
	v_pk_fma_f32 v[174:175], v[118:119], v[142:143], v[174:175]
	v_pk_fma_f32 v[172:173], v[116:117], v[140:141], v[172:173]
	v_pk_fma_f32 v[178:179], v[110:111], v[138:139], v[178:179]
	v_pk_fma_f32 v[176:177], v[108:109], v[136:137], v[176:177]
	v_cvt_pk_bf16_f32 v172, v172, v173
	v_cvt_pk_bf16_f32 v173, v174, v175
	s_nop 0
	v_cvt_pk_bf16_f32 v174, v176, v177
	v_cvt_pk_bf16_f32 v175, v178, v179
	global_load_dwordx4 v[176:179], v[180:181], off offset:256
	s_nop 0
	global_store_dwordx4 v[180:181], v[172:175], off
	s_waitcnt vmcnt(1)
; __device__ __forceinline__ unsigned cvt_pk_bf16(float lo, float hi) { unsigned r; asm volatile("v_cvt_pk_bf16_f32 %0, %1, %2" : "=v"(r) : "v"(lo), "v"(hi)); return r; }
; __device__ __forceinline__ float lo_f(unsigned w) { return __uint_as_float(w << 16); }
; __device__ __forceinline__ float hi_f(unsigned w) { return __uint_as_float(w & 0xffff0000u); }
;     __device__ __forceinline__ void operator()(f32x4 (&acc)[2][2][4][2], const Unit& u, int wr, int wc, int fr, int fq) const {
;     ...
;             for (int m = 0; m < 4; ++m) { const size_t ro = (size_t)(row0 + ai * HALF + m * 16) * DM + col0;
; #pragma unroll
;                 for (int bj = 0; bj < 2; ++bj) { f32x4 x0, x1;
;                     if (Xf32 != nullptr) { x0 = *(const f32x4*)(Xf32 + ro + bj * HALF); x1 = *(const f32x4*)(Xf32 + ro + bj * HALF + 4); }
;                     else { const u32x4 xb = *(const u32x4*)(X + ro + bj * HALF);
;                         x0 = (f32x4){lo_f(xb.x), hi_f(xb.x), lo_f(xb.y), hi_f(xb.y)}; x1 = (f32x4){lo_f(xb.z), hi_f(xb.z), lo_f(xb.w), hi_f(xb.w)}; }
;                     x0 += gv[bj][0] * acc[ai][bj][m][0]; x1 += gv[bj][1] * acc[ai][bj][m][1];
;                     u32x4 w; w.x = cvt_pk_bf16(x0[0], x0[1]); w.y = cvt_pk_bf16(x0[2], x0[3]); w.z = cvt_pk_bf16(x1[0], x1[1]); w.w = cvt_pk_bf16(x1[2], x1[3]);
;                     *(u32x4*)(X + ro + bj * HALF) = w; } }
	s_nop 0
	v_lshlrev_b32_e32 v172, 16, v176
	v_and_b32_e32 v173, 0xffff0000, v176
	v_lshlrev_b32_e32 v174, 16, v177
	v_and_b32_e32 v175, 0xffff0000, v177
	v_lshlrev_b32_e32 v176, 16, v178
	v_and_b32_e32 v177, 0xffff0000, v178
	v_lshlrev_b32_e32 v178, 16, v179
	v_and_b32_e32 v179, 0xffff0000, v179
	v_pk_fma_f32 v[174:175], v[98:99], v[134:135], v[174:175]
	v_pk_fma_f32 v[172:173], v[96:97], v[132:133], v[172:173]
	v_pk_fma_f32 v[178:179], v[90:91], v[130:131], v[178:179]
	v_pk_fma_f32 v[176:177], v[88:89], v[128:129], v[176:177]
	v_cvt_pk_bf16_f32 v172, v172, v173
	v_cvt_pk_bf16_f32 v173, v174, v175
	s_nop 0
	v_cvt_pk_bf16_f32 v174, v176, v177
	v_cvt_pk_bf16_f32 v175, v178, v179
	global_load_dwordx4 v[176:179], v[182:183], off
	s_nop 0
	global_store_dwordx4 v[180:181], v[172:175], off offset:256
	v_or_b32_e32 v180, 48, v160
	v_ashrrev_i32_e32 v181, 31, v180
	v_lshlrev_b64 v[180:181], 12, v[180:181]
	v_lshl_add_u64 v[180:181], s[10:11], 0, v[180:181]
	v_lshl_add_u64 v[164:165], v[180:181], 0, v[164:165]
	v_add_co_u32_e32 v180, vcc, s68, v162
	s_waitcnt vmcnt(1)
	v_lshlrev_b32_e32 v172, 16, v176
	v_and_b32_e32 v173, 0xffff0000, v176
	v_lshlrev_b32_e32 v174, 16, v177
	v_and_b32_e32 v175, 0xffff0000, v177
	v_lshlrev_b32_e32 v176, 16, v178
	v_and_b32_e32 v177, 0xffff0000, v178
	v_lshlrev_b32_e32 v178, 16, v179
	v_and_b32_e32 v179, 0xffff0000, v179
	v_pk_fma_f32 v[174:175], v[102:103], v[142:143], v[174:175]
	v_pk_fma_f32 v[172:173], v[100:101], v[140:141], v[172:173]
	v_pk_fma_f32 v[178:179], v[94:95], v[138:139], v[178:179]
	v_pk_fma_f32 v[176:177], v[92:93], v[136:137], v[176:177]
	v_cvt_pk_bf16_f32 v172, v172, v173
	v_cvt_pk_bf16_f32 v173, v174, v175
	v_addc_co_u32_e32 v181, vcc, 0, v163, vcc
	v_cvt_pk_bf16_f32 v174, v176, v177
	v_cvt_pk_bf16_f32 v175, v178, v179
	global_load_dwordx4 v[176:179], v[182:183], off offset:256
	s_nop 0
	global_store_dwordx4 v[182:183], v[172:175], off
	s_waitcnt vmcnt(1)
	s_nop 0
	v_lshlrev_b32_e32 v172, 16, v176
	v_and_b32_e32 v173, 0xffff0000, v176
	v_lshlrev_b32_e32 v174, 16, v177
	v_and_b32_e32 v175, 0xffff0000, v177
	v_lshlrev_b32_e32 v176, 16, v178
	v_and_b32_e32 v177, 0xffff0000, v178
	v_lshlrev_b32_e32 v178, 16, v179
	v_and_b32_e32 v179, 0xffff0000, v179
	v_pk_fma_f32 v[174:175], v[82:83], v[134:135], v[174:175]
	v_pk_fma_f32 v[172:173], v[80:81], v[132:133], v[172:173]
	v_pk_fma_f32 v[178:179], v[74:75], v[130:131], v[178:179]
	v_pk_fma_f32 v[176:177], v[72:73], v[128:129], v[176:177]
	v_cvt_pk_bf16_f32 v172, v172, v173
	v_cvt_pk_bf16_f32 v173, v174, v175
	s_nop 0
	v_cvt_pk_bf16_f32 v174, v176, v177
	v_cvt_pk_bf16_f32 v175, v178, v179
	global_load_dwordx4 v[176:179], v[164:165], off
	s_nop 0
	global_store_dwordx4 v[182:183], v[172:175], off offset:256
	v_lshl_add_u64 v[182:183], v[162:163], 0, s[18:19]
	s_waitcnt vmcnt(1)
	v_lshlrev_b32_e32 v172, 16, v176
	v_and_b32_e32 v173, 0xffff0000, v176
	v_lshlrev_b32_e32 v174, 16, v177
	v_and_b32_e32 v175, 0xffff0000, v177
	v_lshlrev_b32_e32 v176, 16, v178
	v_and_b32_e32 v177, 0xffff0000, v178
	v_lshlrev_b32_e32 v178, 16, v179
	v_and_b32_e32 v179, 0xffff0000, v179
	v_pk_fma_f32 v[174:175], v[86:87], v[142:143], v[174:175]
	v_pk_fma_f32 v[172:173], v[84:85], v[140:141], v[172:173]
	v_pk_fma_f32 v[178:179], v[78:79], v[138:139], v[178:179]
	v_pk_fma_f32 v[176:177], v[76:77], v[136:137], v[176:177]
	v_cvt_pk_bf16_f32 v172, v172, v173
	v_cvt_pk_bf16_f32 v173, v174, v175
	s_nop 0
	v_cvt_pk_bf16_f32 v174, v176, v177
	v_cvt_pk_bf16_f32 v175, v178, v179
	global_load_dwordx4 v[176:179], v[164:165], off offset:256
	s_nop 0
	global_store_dwordx4 v[164:165], v[172:175], off
	s_waitcnt vmcnt(1)
	s_nop 0
	v_lshlrev_b32_e32 v172, 16, v176
	v_and_b32_e32 v173, 0xffff0000, v176
	v_lshlrev_b32_e32 v174, 16, v177
	v_and_b32_e32 v175, 0xffff0000, v177
	v_lshlrev_b32_e32 v176, 16, v178
	v_and_b32_e32 v177, 0xffff0000, v178
	v_lshlrev_b32_e32 v178, 16, v179
	v_and_b32_e32 v179, 0xffff0000, v179
	v_pk_fma_f32 v[174:175], v[70:71], v[134:135], v[174:175]
	v_pk_fma_f32 v[172:173], v[68:69], v[132:133], v[172:173]
	v_pk_fma_f32 v[178:179], v[66:67], v[130:131], v[178:179]
	v_pk_fma_f32 v[176:177], v[64:65], v[128:129], v[176:177]
	v_cvt_pk_bf16_f32 v172, v172, v173
	v_cvt_pk_bf16_f32 v173, v174, v175
	s_nop 0
	v_cvt_pk_bf16_f32 v174, v176, v177
	v_cvt_pk_bf16_f32 v175, v178, v179
	global_load_dwordx4 v[176:179], v[180:181], off
	s_nop 0
	global_store_dwordx4 v[164:165], v[172:175], off offset:256
	s_waitcnt vmcnt(1)
	v_lshlrev_b32_e32 v164, 16, v176
	v_and_b32_e32 v165, 0xffff0000, v176
	v_lshlrev_b32_e32 v172, 16, v177
	v_and_b32_e32 v173, 0xffff0000, v177
	v_lshlrev_b32_e32 v174, 16, v178
	v_and_b32_e32 v175, 0xffff0000, v178
	v_lshlrev_b32_e32 v176, 16, v179
	v_and_b32_e32 v177, 0xffff0000, v179
	v_pk_fma_f32 v[178:179], v[62:63], v[142:143], v[172:173]
	v_pk_fma_f32 v[176:177], v[58:59], v[138:139], v[176:177]
	v_pk_fma_f32 v[174:175], v[56:57], v[136:137], v[174:175]
	v_pk_fma_f32 v[164:165], v[60:61], v[140:141], v[164:165]
	s_nop 0
	v_cvt_pk_bf16_f32 v172, v164, v165
	v_cvt_pk_bf16_f32 v173, v178, v179
	v_cvt_pk_bf16_f32 v174, v174, v175
	v_cvt_pk_bf16_f32 v175, v176, v177
	global_load_dwordx4 v[176:179], v[182:183], off offset:256
	v_add_co_u32_e32 v164, vcc, s69, v162
	global_store_dwordx4 v[180:181], v[172:175], off
	s_nop 0
	v_addc_co_u32_e32 v165, vcc, 0, v163, vcc
	v_lshl_add_u64 v[180:181], v[162:163], 0, s[20:21]
	s_waitcnt vmcnt(1)
; __device__ __forceinline__ unsigned cvt_pk_bf16(float lo, float hi) { unsigned r; asm volatile("v_cvt_pk_bf16_f32 %0, %1, %2" : "=v"(r) : "v"(lo), "v"(hi)); return r; }
; __device__ __forceinline__ float lo_f(unsigned w) { return __uint_as_float(w << 16); }
; __device__ __forceinline__ float hi_f(unsigned w) { return __uint_as_float(w & 0xffff0000u); }
;     __device__ __forceinline__ void operator()(f32x4 (&acc)[2][2][4][2], const Unit& u, int wr, int wc, int fr, int fq) const {
;     ...
;             for (int m = 0; m < 4; ++m) { const size_t ro = (size_t)(row0 + ai * HALF + m * 16) * DM + col0;
; #pragma unroll
;                 for (int bj = 0; bj < 2; ++bj) { f32x4 x0, x1;
;                     if (Xf32 != nullptr) { x0 = *(const f32x4*)(Xf32 + ro + bj * HALF); x1 = *(const f32x4*)(Xf32 + ro + bj * HALF + 4); }
;                     else { const u32x4 xb = *(const u32x4*)(X + ro + bj * HALF);
;                         x0 = (f32x4){lo_f(xb.x), hi_f(xb.x), lo_f(xb.y), hi_f(xb.y)}; x1 = (f32x4){lo_f(xb.z), hi_f(xb.z), lo_f(xb.w), hi_f(xb.w)}; }
;                     x0 += gv[bj][0] * acc[ai][bj][m][0]; x1 += gv[bj][1] * acc[ai][bj][m][1];
;                     u32x4 w; w.x = cvt_pk_bf16(x0[0], x0[1]); w.y = cvt_pk_bf16(x0[2], x0[3]); w.z = cvt_pk_bf16(x1[0], x1[1]); w.w = cvt_pk_bf16(x1[2], x1[3]);
;                     *(u32x4*)(X + ro + bj * HALF) = w; } }
	v_lshlrev_b32_e32 v172, 16, v176
	v_and_b32_e32 v173, 0xffff0000, v176
	v_lshlrev_b32_e32 v174, 16, v177
	v_and_b32_e32 v175, 0xffff0000, v177
	v_lshlrev_b32_e32 v176, 16, v178
	v_and_b32_e32 v177, 0xffff0000, v178
	v_lshlrev_b32_e32 v178, 16, v179
	v_and_b32_e32 v179, 0xffff0000, v179
	v_pk_fma_f32 v[174:175], v[50:51], v[134:135], v[174:175]
	v_pk_fma_f32 v[172:173], v[48:49], v[132:133], v[172:173]
	v_pk_fma_f32 v[178:179], v[42:43], v[130:131], v[178:179]
	v_pk_fma_f32 v[176:177], v[40:41], v[128:129], v[176:177]
	v_cvt_pk_bf16_f32 v172, v172, v173
	v_cvt_pk_bf16_f32 v173, v174, v175
	s_nop 0
	v_cvt_pk_bf16_f32 v174, v176, v177
	v_cvt_pk_bf16_f32 v175, v178, v179
	global_load_dwordx4 v[176:179], v[164:165], off
	s_nop 0
	global_store_dwordx4 v[182:183], v[172:175], off offset:256
	v_add_co_u32_e32 v182, vcc, s70, v162
	s_waitcnt vmcnt(1)
	v_lshlrev_b32_e32 v172, 16, v176
	v_and_b32_e32 v173, 0xffff0000, v176
	v_lshlrev_b32_e32 v174, 16, v177
	v_and_b32_e32 v175, 0xffff0000, v177
	v_lshlrev_b32_e32 v176, 16, v178
	v_and_b32_e32 v177, 0xffff0000, v178
	v_lshlrev_b32_e32 v178, 16, v179
	v_and_b32_e32 v179, 0xffff0000, v179
	v_pk_fma_f32 v[174:175], v[54:55], v[142:143], v[174:175]
	v_pk_fma_f32 v[172:173], v[52:53], v[140:141], v[172:173]
	v_pk_fma_f32 v[178:179], v[46:47], v[138:139], v[178:179]
	v_pk_fma_f32 v[176:177], v[44:45], v[136:137], v[176:177]
	v_cvt_pk_bf16_f32 v172, v172, v173
	v_cvt_pk_bf16_f32 v173, v174, v175
	v_addc_co_u32_e32 v183, vcc, 0, v163, vcc
	v_cvt_pk_bf16_f32 v174, v176, v177
	v_cvt_pk_bf16_f32 v175, v178, v179
	global_load_dwordx4 v[176:179], v[180:181], off offset:256
	s_nop 0
	global_store_dwordx4 v[164:165], v[172:175], off
	s_waitcnt vmcnt(1)
	v_lshlrev_b32_e32 v164, 16, v176
	v_and_b32_e32 v165, 0xffff0000, v176
	v_lshlrev_b32_e32 v172, 16, v177
	v_and_b32_e32 v173, 0xffff0000, v177
	v_lshlrev_b32_e32 v174, 16, v178
	v_and_b32_e32 v175, 0xffff0000, v178
	v_lshlrev_b32_e32 v176, 16, v179
	v_and_b32_e32 v177, 0xffff0000, v179
	v_pk_fma_f32 v[178:179], v[34:35], v[134:135], v[172:173]
	v_pk_fma_f32 v[176:177], v[26:27], v[130:131], v[176:177]
	v_pk_fma_f32 v[174:175], v[24:25], v[128:129], v[174:175]
	v_pk_fma_f32 v[164:165], v[32:33], v[132:133], v[164:165]
	s_nop 0
	v_cvt_pk_bf16_f32 v172, v164, v165
	v_cvt_pk_bf16_f32 v173, v178, v179
	v_cvt_pk_bf16_f32 v174, v174, v175
	v_cvt_pk_bf16_f32 v175, v176, v177
	global_load_dwordx4 v[176:179], v[182:183], off
	v_lshl_add_u64 v[164:165], v[162:163], 0, s[22:23]
	global_store_dwordx4 v[180:181], v[172:175], off offset:256
	v_add_co_u32_e32 v180, vcc, s71, v162
	s_waitcnt vmcnt(1)
	v_lshlrev_b32_e32 v172, 16, v176
	v_and_b32_e32 v173, 0xffff0000, v176
	v_lshlrev_b32_e32 v174, 16, v177
	v_and_b32_e32 v175, 0xffff0000, v177
	v_lshlrev_b32_e32 v176, 16, v178
	v_and_b32_e32 v177, 0xffff0000, v178
	v_lshlrev_b32_e32 v178, 16, v179
	v_and_b32_e32 v179, 0xffff0000, v179
	v_pk_fma_f32 v[174:175], v[38:39], v[142:143], v[174:175]
	v_pk_fma_f32 v[172:173], v[36:37], v[140:141], v[172:173]
	v_pk_fma_f32 v[178:179], v[30:31], v[138:139], v[178:179]
	v_pk_fma_f32 v[176:177], v[28:29], v[136:137], v[176:177]
	v_cvt_pk_bf16_f32 v172, v172, v173
	v_cvt_pk_bf16_f32 v173, v174, v175
	v_addc_co_u32_e32 v181, vcc, 0, v163, vcc
	v_cvt_pk_bf16_f32 v174, v176, v177
	v_cvt_pk_bf16_f32 v175, v178, v179
	global_load_dwordx4 v[176:179], v[164:165], off offset:256
	s_nop 0
	global_store_dwordx4 v[182:183], v[172:175], off
	v_lshl_add_u64 v[182:183], v[162:163], 0, s[24:25]
	s_waitcnt vmcnt(1)
	v_lshlrev_b32_e32 v172, 16, v176
	v_and_b32_e32 v173, 0xffff0000, v176
	v_lshlrev_b32_e32 v174, 16, v177
	v_and_b32_e32 v175, 0xffff0000, v177
	v_lshlrev_b32_e32 v176, 16, v178
	v_and_b32_e32 v177, 0xffff0000, v178
	v_lshlrev_b32_e32 v178, 16, v179
	v_and_b32_e32 v179, 0xffff0000, v179
	v_pk_fma_f32 v[174:175], v[18:19], v[134:135], v[174:175]
	v_pk_fma_f32 v[172:173], v[16:17], v[132:133], v[172:173]
	v_pk_fma_f32 v[178:179], v[10:11], v[130:131], v[178:179]
	v_pk_fma_f32 v[176:177], v[8:9], v[128:129], v[176:177]
	v_cvt_pk_bf16_f32 v172, v172, v173
	v_cvt_pk_bf16_f32 v173, v174, v175
	s_nop 0
	v_cvt_pk_bf16_f32 v174, v176, v177
	v_cvt_pk_bf16_f32 v175, v178, v179
	global_load_dwordx4 v[176:179], v[180:181], off
	s_waitcnt vmcnt(0)
	v_lshlrev_b32_e32 v162, 16, v176
	global_store_dwordx4 v[164:165], v[172:175], off offset:256
	v_and_b32_e32 v163, 0xffff0000, v176
	v_lshlrev_b32_e32 v164, 16, v177
	v_and_b32_e32 v165, 0xffff0000, v177
	v_lshlrev_b32_e32 v172, 16, v178
	v_and_b32_e32 v173, 0xffff0000, v178
	v_lshlrev_b32_e32 v174, 16, v179
	v_and_b32_e32 v175, 0xffff0000, v179
	v_pk_fma_f32 v[164:165], v[22:23], v[142:143], v[164:165]
	v_pk_fma_f32 v[162:163], v[20:21], v[140:141], v[162:163]
	v_pk_fma_f32 v[174:175], v[14:15], v[138:139], v[174:175]
	v_pk_fma_f32 v[172:173], v[12:13], v[136:137], v[172:173]
	v_cvt_pk_bf16_f32 v162, v162, v163
	v_cvt_pk_bf16_f32 v163, v164, v165
	s_nop 0
	v_cvt_pk_bf16_f32 v164, v172, v173
	v_cvt_pk_bf16_f32 v165, v174, v175
	global_load_dwordx4 v[172:175], v[182:183], off offset:256
	s_nop 0
	global_store_dwordx4 v[180:181], v[162:165], off
	s_waitcnt vmcnt(1)
	s_nop 0
	v_lshlrev_b32_e32 v162, 16, v172
	v_and_b32_e32 v163, 0xffff0000, v172
	v_lshlrev_b32_e32 v164, 16, v173
	v_and_b32_e32 v165, 0xffff0000, v173
	v_lshlrev_b32_e32 v172, 16, v174
	v_and_b32_e32 v173, 0xffff0000, v174
	v_lshlrev_b32_e32 v174, 16, v175
	v_and_b32_e32 v175, 0xffff0000, v175
	v_pk_fma_f32 v[164:165], v[6:7], v[134:135], v[164:165]
	v_pk_fma_f32 v[162:163], v[4:5], v[132:133], v[162:163]
	v_pk_fma_f32 v[174:175], v[2:3], v[130:131], v[174:175]
	v_pk_fma_f32 v[172:173], v[0:1], v[128:129], v[172:173]
	v_cvt_pk_bf16_f32 v162, v162, v163
	v_cvt_pk_bf16_f32 v163, v164, v165
	s_nop 0
	v_cvt_pk_bf16_f32 v164, v172, v173
	v_cvt_pk_bf16_f32 v165, v174, v175
	global_store_dwordx4 v[182:183], v[162:165], off offset:256
	s_cbranch_execz .LBB0_1127

; __device__ __forceinline__ unsigned cvt_pk_bf16(float lo, float hi) { unsigned r; asm volatile("v_cvt_pk_bf16_f32 %0, %1, %2" : "=v"(r) : "v"(lo), "v"(hi)); return r; }
; __device__ __forceinline__ float lo_f(unsigned w) { return __uint_as_float(w << 16); }
; __device__ __forceinline__ float hi_f(unsigned w) { return __uint_as_float(w & 0xffff0000u); }
;     __device__ __forceinline__ void operator()(f32x4 (&acc)[2][2][4][2], const Unit& u, int wr, int wc, int fr, int fq) const {
;         const int row0 = u.pm * BM + wr * 64 + fr, col0 = u.pn * BM + wc * 32 + 8 * fq;
;         const int r = u.pm < 32 ? (u.pm >> 3) : 4;
;         const float* gt = mod + (size_t)r * MODW + gate_off + col0;
;         f32x4 gv[2][2];
; #pragma unroll
;         for (int bj = 0; bj < 2; ++bj)
; #pragma unroll
;             for (int n = 0; n < 2; ++n) gv[bj][n] = *(const f32x4*)(gt + bj * HALF + 4 * n);
;         if (u.ks >= 0) {
;             float* pb = PART + ((size_t)u.ks * TC + (size_t)(row0 - TL)) * DM + col0;
; #pragma unroll
;             for (int ai = 0; ai < 2; ++ai)
; #pragma unroll
;                 for (int m = 0; m < 4; ++m)
; #pragma unroll
;                     for (int bj = 0; bj < 2; ++bj) { float* q = pb + (size_t)(ai * HALF + m * 16) * DM + bj * HALF;
;                         *(f32x4*)q = gv[bj][0] * acc[ai][bj][m][0]; *(f32x4*)(q + 4) = gv[bj][1] * acc[ai][bj][m][1]; }
;             return;
;         }
; #pragma unroll
;         for (int ai = 0; ai < 2; ++ai)
; #pragma unroll
;             for (int m = 0; m < 4; ++m) { const size_t ro = (size_t)(row0 + ai * HALF + m * 16) * DM + col0;
; #pragma unroll
;                 for (int bj = 0; bj < 2; ++bj) { f32x4 x0, x1;
;                     if (Xf32 != nullptr) { x0 = *(const f32x4*)(Xf32 + ro + bj * HALF); x1 = *(const f32x4*)(Xf32 + ro + bj * HALF + 4); }
;                     else { const u32x4 xb = *(const u32x4*)(X + ro + bj * HALF);
;                         x0 = (f32x4){lo_f(xb.x), hi_f(xb.x), lo_f(xb.y), hi_f(xb.y)}; x1 = (f32x4){lo_f(xb.z), hi_f(xb.z), lo_f(xb.w), hi_f(xb.w)}; }
;                     x0 += gv[bj][0] * acc[ai][bj][m][0]; x1 += gv[bj][1] * acc[ai][bj][m][1];
;                     u32x4 w; w.x = cvt_pk_bf16(x0[0], x0[1]); w.y = cvt_pk_bf16(x0[2], x0[3]); w.z = cvt_pk_bf16(x1[0], x1[1]); w.w = cvt_pk_bf16(x1[2], x1[3]);
;                     *(u32x4*)(X + ro + bj * HALF) = w; } }
.LBB0_1695:
	v_lshl_add_u32 v160, s36, 8, v164
	s_lshl_b64 s[42:43], s[42:43], 2
	v_lshl_or_b32 v120, s70, 8, v166
	s_add_u32 s42, s2, s42
	v_ashrrev_i32_e32 v161, 31, v160
	v_ashrrev_i32_e32 v121, 31, v120
	v_lshlrev_b64 v[122:123], 12, v[160:161]
	s_addc_u32 s43, s3, s43
	v_lshl_add_u64 v[122:123], s[8:9], 0, v[122:123]
	v_lshlrev_b64 v[162:163], 1, v[120:121]
	v_lshl_add_u64 v[120:121], v[120:121], 2, s[42:43]
	v_lshl_add_u64 v[158:159], v[122:123], 0, v[162:163]
	v_add_co_u32_e32 v122, vcc, s65, v120
	global_load_dwordx4 v[170:173], v[158:159], off
	global_load_dword v244, v[158:159], off
	global_load_dword v244, v[158:159], off offset:256
	v_mov_b32_e32 v240, 0x10000
	v_mov_b32_e32 v241, 0
	v_lshl_add_u64 v[242:243], v[158:159], 0, v[240:241]
	global_load_dword v244, v[242:243], off
	global_load_dword v244, v[242:243], off offset:256
	v_lshl_add_u64 v[242:243], v[242:243], 0, v[240:241]
	global_load_dword v244, v[242:243], off
	global_load_dword v244, v[242:243], off offset:256
	v_lshl_add_u64 v[242:243], v[242:243], 0, v[240:241]
	global_load_dword v244, v[242:243], off
	global_load_dword v244, v[242:243], off offset:256
	v_mov_b32_e32 v240, 0x50000
	v_lshl_add_u64 v[242:243], v[242:243], 0, v[240:241]
	global_load_dword v244, v[242:243], off
	global_load_dword v244, v[242:243], off offset:256
	v_mov_b32_e32 v240, 0x10000
	v_lshl_add_u64 v[242:243], v[242:243], 0, v[240:241]
	global_load_dword v244, v[242:243], off
	global_load_dword v244, v[242:243], off offset:256
	v_lshl_add_u64 v[242:243], v[242:243], 0, v[240:241]
	global_load_dword v244, v[242:243], off
	global_load_dword v244, v[242:243], off offset:256
	v_lshl_add_u64 v[242:243], v[242:243], 0, v[240:241]
	global_load_dword v244, v[242:243], off
	global_load_dword v244, v[242:243], off offset:256
	s_nop 0
	v_addc_co_u32_e32 v123, vcc, 0, v121, vcc
	global_load_dwordx4 v[132:135], v[122:123], off
	v_lshl_add_u64 v[124:125], v[120:121], 0, s[16:17]
	global_load_dwordx4 v[128:131], v[124:125], off offset:16
	global_load_dwordx4 v[120:123], v[124:125], off offset:528
	s_nop 0
	global_load_dwordx4 v[124:127], v[124:125], off offset:512
	s_waitcnt vmcnt(0)
	v_lshlrev_b32_e32 v174, 16, v170
	v_and_b32_e32 v175, 0xffff0000, v170
	v_lshlrev_b32_e32 v170, 16, v171
	v_and_b32_e32 v171, 0xffff0000, v171
	v_lshlrev_b32_e32 v176, 16, v172
	v_and_b32_e32 v177, 0xffff0000, v172
	v_lshlrev_b32_e32 v172, 16, v173
	v_and_b32_e32 v173, 0xffff0000, v173
	v_pk_fma_f32 v[142:143], v[142:143], v[134:135], v[170:171]
	v_pk_fma_f32 v[140:141], v[140:141], v[132:133], v[174:175]
	v_pk_fma_f32 v[170:171], v[138:139], v[130:131], v[172:173]
	v_pk_fma_f32 v[138:139], v[136:137], v[128:129], v[176:177]
	v_cvt_pk_bf16_f32 v136, v140, v141
	v_cvt_pk_bf16_f32 v137, v142, v143
	s_nop 0
	v_cvt_pk_bf16_f32 v138, v138, v139
	v_cvt_pk_bf16_f32 v139, v170, v171
	global_load_dwordx4 v[140:143], v[158:159], off offset:256
	v_or_b32_e32 v170, 16, v160
	v_ashrrev_i32_e32 v171, 31, v170
	v_lshlrev_b64 v[170:171], 12, v[170:171]
	v_lshl_add_u64 v[170:171], s[8:9], 0, v[170:171]
	global_store_dwordx4 v[158:159], v[136:139], off
	v_lshl_add_u64 v[170:171], v[170:171], 0, v[162:163]
	s_waitcnt vmcnt(1)
	v_lshlrev_b32_e32 v136, 16, v140
	v_and_b32_e32 v137, 0xffff0000, v140
	v_lshlrev_b32_e32 v138, 16, v141
	v_and_b32_e32 v139, 0xffff0000, v141
	v_lshlrev_b32_e32 v140, 16, v142
	v_and_b32_e32 v141, 0xffff0000, v142
	v_lshlrev_b32_e32 v142, 16, v143
	v_and_b32_e32 v143, 0xffff0000, v143
	v_pk_fma_f32 v[114:115], v[114:115], v[126:127], v[138:139]
	v_pk_fma_f32 v[112:113], v[112:113], v[124:125], v[136:137]
	v_pk_fma_f32 v[136:137], v[110:111], v[122:123], v[142:143]
	v_pk_fma_f32 v[110:111], v[108:109], v[120:121], v[140:141]
	v_cvt_pk_bf16_f32 v108, v112, v113
	v_cvt_pk_bf16_f32 v109, v114, v115
	s_nop 0
	v_cvt_pk_bf16_f32 v110, v110, v111
	v_cvt_pk_bf16_f32 v111, v136, v137
	global_load_dwordx4 v[112:115], v[170:171], off
	s_nop 0
	global_store_dwordx4 v[158:159], v[108:111], off offset:256
	s_waitcnt vmcnt(1)
	s_nop 0
	v_lshlrev_b32_e32 v108, 16, v112
	v_and_b32_e32 v109, 0xffff0000, v112
	v_lshlrev_b32_e32 v110, 16, v113
	v_and_b32_e32 v111, 0xffff0000, v113
	v_lshlrev_b32_e32 v112, 16, v114
	v_and_b32_e32 v113, 0xffff0000, v114
	v_lshlrev_b32_e32 v114, 16, v115
	v_and_b32_e32 v115, 0xffff0000, v115
	v_pk_fma_f32 v[110:111], v[118:119], v[134:135], v[110:111]
	v_pk_fma_f32 v[108:109], v[116:117], v[132:133], v[108:109]
	v_pk_fma_f32 v[114:115], v[106:107], v[130:131], v[114:115]
	v_pk_fma_f32 v[106:107], v[104:105], v[128:129], v[112:113]
	v_cvt_pk_bf16_f32 v104, v108, v109
	v_cvt_pk_bf16_f32 v105, v110, v111
	v_or_b32_e32 v112, 32, v160
	v_cvt_pk_bf16_f32 v106, v106, v107
	v_cvt_pk_bf16_f32 v107, v114, v115
	global_load_dwordx4 v[108:111], v[170:171], off offset:256
	v_ashrrev_i32_e32 v113, 31, v112
	v_lshlrev_b64 v[112:113], 12, v[112:113]
	v_lshl_add_u64 v[112:113], s[8:9], 0, v[112:113]
	global_store_dwordx4 v[170:171], v[104:107], off
	v_lshl_add_u64 v[112:113], v[112:113], 0, v[162:163]
	s_waitcnt vmcnt(1)
	v_lshlrev_b32_e32 v104, 16, v108
	v_and_b32_e32 v105, 0xffff0000, v108
	v_lshlrev_b32_e32 v106, 16, v109
	v_and_b32_e32 v107, 0xffff0000, v109
	v_lshlrev_b32_e32 v108, 16, v110
	v_and_b32_e32 v109, 0xffff0000, v110
	v_lshlrev_b32_e32 v110, 16, v111
	v_and_b32_e32 v111, 0xffff0000, v111
	v_pk_fma_f32 v[98:99], v[98:99], v[126:127], v[106:107]
	v_pk_fma_f32 v[96:97], v[96:97], v[124:125], v[104:105]
	v_pk_fma_f32 v[104:105], v[94:95], v[122:123], v[110:111]
	v_pk_fma_f32 v[94:95], v[92:93], v[120:121], v[108:109]
	v_cvt_pk_bf16_f32 v92, v96, v97
	v_cvt_pk_bf16_f32 v93, v98, v99
	s_nop 0
	v_cvt_pk_bf16_f32 v94, v94, v95
	v_cvt_pk_bf16_f32 v95, v104, v105
	global_load_dwordx4 v[96:99], v[112:113], off
	s_nop 0
	global_store_dwordx4 v[170:171], v[92:95], off offset:256
	s_waitcnt vmcnt(1)
; __device__ __forceinline__ unsigned cvt_pk_bf16(float lo, float hi) { unsigned r; asm volatile("v_cvt_pk_bf16_f32 %0, %1, %2" : "=v"(r) : "v"(lo), "v"(hi)); return r; }
; __device__ __forceinline__ float lo_f(unsigned w) { return __uint_as_float(w << 16); }
; __device__ __forceinline__ float hi_f(unsigned w) { return __uint_as_float(w & 0xffff0000u); }
;     __device__ __forceinline__ void operator()(f32x4 (&acc)[2][2][4][2], const Unit& u, int wr, int wc, int fr, int fq) const {
;     ...
;         for (int ai = 0; ai < 2; ++ai)
; #pragma unroll
;             for (int m = 0; m < 4; ++m) { const size_t ro = (size_t)(row0 + ai * HALF + m * 16) * DM + col0;
; #pragma unroll
;                 for (int bj = 0; bj < 2; ++bj) { f32x4 x0, x1;
;                     if (Xf32 != nullptr) { x0 = *(const f32x4*)(Xf32 + ro + bj * HALF); x1 = *(const f32x4*)(Xf32 + ro + bj * HALF + 4); }
;                     else { const u32x4 xb = *(const u32x4*)(X + ro + bj * HALF);
;                         x0 = (f32x4){lo_f(xb.x), hi_f(xb.x), lo_f(xb.y), hi_f(xb.y)}; x1 = (f32x4){lo_f(xb.z), hi_f(xb.z), lo_f(xb.w), hi_f(xb.w)}; }
;                     x0 += gv[bj][0] * acc[ai][bj][m][0]; x1 += gv[bj][1] * acc[ai][bj][m][1];
;                     u32x4 w; w.x = cvt_pk_bf16(x0[0], x0[1]); w.y = cvt_pk_bf16(x0[2], x0[3]); w.z = cvt_pk_bf16(x1[0], x1[1]); w.w = cvt_pk_bf16(x1[2], x1[3]);
;                     *(u32x4*)(X + ro + bj * HALF) = w; } }
	s_nop 0
	v_lshlrev_b32_e32 v92, 16, v96
	v_and_b32_e32 v93, 0xffff0000, v96
	v_lshlrev_b32_e32 v94, 16, v97
	v_and_b32_e32 v95, 0xffff0000, v97
	v_lshlrev_b32_e32 v96, 16, v98
	v_and_b32_e32 v97, 0xffff0000, v98
	v_lshlrev_b32_e32 v98, 16, v99
	v_and_b32_e32 v99, 0xffff0000, v99
	v_pk_fma_f32 v[94:95], v[102:103], v[134:135], v[94:95]
	v_pk_fma_f32 v[92:93], v[100:101], v[132:133], v[92:93]
	v_pk_fma_f32 v[98:99], v[90:91], v[130:131], v[98:99]
	v_pk_fma_f32 v[90:91], v[88:89], v[128:129], v[96:97]
	v_cvt_pk_bf16_f32 v88, v92, v93
	v_cvt_pk_bf16_f32 v89, v94, v95
	v_or_b32_e32 v96, 48, v160
	v_cvt_pk_bf16_f32 v90, v90, v91
	v_cvt_pk_bf16_f32 v91, v98, v99
	global_load_dwordx4 v[92:95], v[112:113], off offset:256
	v_ashrrev_i32_e32 v97, 31, v96
	v_lshlrev_b64 v[96:97], 12, v[96:97]
	v_lshl_add_u64 v[96:97], s[8:9], 0, v[96:97]
	global_store_dwordx4 v[112:113], v[88:91], off
	v_lshl_add_u64 v[96:97], v[96:97], 0, v[162:163]
	s_waitcnt vmcnt(1)
	v_lshlrev_b32_e32 v88, 16, v92
	v_and_b32_e32 v89, 0xffff0000, v92
	v_lshlrev_b32_e32 v90, 16, v93
	v_and_b32_e32 v91, 0xffff0000, v93
	v_lshlrev_b32_e32 v92, 16, v94
	v_and_b32_e32 v93, 0xffff0000, v94
	v_lshlrev_b32_e32 v94, 16, v95
	v_and_b32_e32 v95, 0xffff0000, v95
	v_pk_fma_f32 v[82:83], v[82:83], v[126:127], v[90:91]
	v_pk_fma_f32 v[80:81], v[80:81], v[124:125], v[88:89]
	v_pk_fma_f32 v[88:89], v[78:79], v[122:123], v[94:95]
	v_pk_fma_f32 v[78:79], v[76:77], v[120:121], v[92:93]
	v_cvt_pk_bf16_f32 v76, v80, v81
	v_cvt_pk_bf16_f32 v77, v82, v83
	s_nop 0
	v_cvt_pk_bf16_f32 v78, v78, v79
	v_cvt_pk_bf16_f32 v79, v88, v89
	global_load_dwordx4 v[80:83], v[96:97], off
	s_nop 0
	global_store_dwordx4 v[112:113], v[76:79], off offset:256
	s_waitcnt vmcnt(1)
	s_nop 0
	v_lshlrev_b32_e32 v76, 16, v80
	v_and_b32_e32 v77, 0xffff0000, v80
	v_lshlrev_b32_e32 v78, 16, v81
	v_and_b32_e32 v79, 0xffff0000, v81
	v_lshlrev_b32_e32 v80, 16, v82
	v_and_b32_e32 v81, 0xffff0000, v82
	v_lshlrev_b32_e32 v82, 16, v83
	v_and_b32_e32 v83, 0xffff0000, v83
	v_pk_fma_f32 v[78:79], v[86:87], v[134:135], v[78:79]
	v_pk_fma_f32 v[76:77], v[84:85], v[132:133], v[76:77]
	v_pk_fma_f32 v[82:83], v[74:75], v[130:131], v[82:83]
	v_pk_fma_f32 v[74:75], v[72:73], v[128:129], v[80:81]
	v_cvt_pk_bf16_f32 v72, v76, v77
	v_cvt_pk_bf16_f32 v73, v78, v79
	v_add_co_u32_e32 v80, vcc, s66, v158
	v_cvt_pk_bf16_f32 v74, v74, v75
	v_cvt_pk_bf16_f32 v75, v82, v83
	global_load_dwordx4 v[76:79], v[96:97], off offset:256
	s_nop 0
	v_addc_co_u32_e32 v81, vcc, 0, v159, vcc
	global_store_dwordx4 v[96:97], v[72:75], off
	s_waitcnt vmcnt(1)
	s_nop 0
	v_lshlrev_b32_e32 v72, 16, v76
	v_and_b32_e32 v73, 0xffff0000, v76
	v_lshlrev_b32_e32 v74, 16, v77
	v_and_b32_e32 v75, 0xffff0000, v77
	v_lshlrev_b32_e32 v76, 16, v78
	v_and_b32_e32 v77, 0xffff0000, v78
	v_lshlrev_b32_e32 v78, 16, v79
	v_and_b32_e32 v79, 0xffff0000, v79
	v_pk_fma_f32 v[70:71], v[70:71], v[126:127], v[74:75]
	v_pk_fma_f32 v[68:69], v[68:69], v[124:125], v[72:73]
	v_pk_fma_f32 v[72:73], v[66:67], v[122:123], v[78:79]
	v_pk_fma_f32 v[66:67], v[64:65], v[120:121], v[76:77]
	v_cvt_pk_bf16_f32 v64, v68, v69
	v_cvt_pk_bf16_f32 v65, v70, v71
	s_nop 0
	v_cvt_pk_bf16_f32 v66, v66, v67
	v_cvt_pk_bf16_f32 v67, v72, v73
	global_load_dwordx4 v[68:71], v[80:81], off
	v_lshl_add_u64 v[72:73], v[158:159], 0, s[4:5]
	global_store_dwordx4 v[96:97], v[64:67], off offset:256
	s_waitcnt vmcnt(1)
	s_nop 0
	v_lshlrev_b32_e32 v64, 16, v68
	v_and_b32_e32 v65, 0xffff0000, v68
	v_lshlrev_b32_e32 v66, 16, v69
	v_and_b32_e32 v67, 0xffff0000, v69
	v_lshlrev_b32_e32 v68, 16, v70
	v_and_b32_e32 v69, 0xffff0000, v70
	v_lshlrev_b32_e32 v70, 16, v71
	v_and_b32_e32 v71, 0xffff0000, v71
	v_pk_fma_f32 v[62:63], v[62:63], v[134:135], v[66:67]
	v_pk_fma_f32 v[60:61], v[60:61], v[132:133], v[64:65]
	v_pk_fma_f32 v[64:65], v[58:59], v[130:131], v[70:71]
	v_pk_fma_f32 v[58:59], v[56:57], v[128:129], v[68:69]
	v_cvt_pk_bf16_f32 v56, v60, v61
	v_cvt_pk_bf16_f32 v57, v62, v63
	s_nop 0
	v_cvt_pk_bf16_f32 v58, v58, v59
	v_cvt_pk_bf16_f32 v59, v64, v65
	global_load_dwordx4 v[60:63], v[72:73], off offset:256
	v_add_co_u32_e32 v64, vcc, s67, v158
	global_store_dwordx4 v[80:81], v[56:59], off
	s_nop 0
	v_addc_co_u32_e32 v65, vcc, 0, v159, vcc
	s_waitcnt vmcnt(1)
	v_lshlrev_b32_e32 v56, 16, v60
	v_and_b32_e32 v57, 0xffff0000, v60
	v_lshlrev_b32_e32 v58, 16, v61
	v_and_b32_e32 v59, 0xffff0000, v61
	v_lshlrev_b32_e32 v60, 16, v62
	v_and_b32_e32 v61, 0xffff0000, v62
	v_lshlrev_b32_e32 v62, 16, v63
	v_and_b32_e32 v63, 0xffff0000, v63
	v_pk_fma_f32 v[54:55], v[54:55], v[126:127], v[58:59]
	v_pk_fma_f32 v[52:53], v[52:53], v[124:125], v[56:57]
	v_pk_fma_f32 v[56:57], v[46:47], v[122:123], v[62:63]
	v_pk_fma_f32 v[46:47], v[44:45], v[120:121], v[60:61]
	v_cvt_pk_bf16_f32 v44, v52, v53
	v_cvt_pk_bf16_f32 v45, v54, v55
	s_nop 0
	v_cvt_pk_bf16_f32 v46, v46, v47
	v_cvt_pk_bf16_f32 v47, v56, v57
	global_load_dwordx4 v[52:55], v[64:65], off
	v_lshl_add_u64 v[56:57], v[158:159], 0, s[18:19]
	global_store_dwordx4 v[72:73], v[44:47], off offset:256
	s_waitcnt vmcnt(1)
; __device__ __forceinline__ unsigned cvt_pk_bf16(float lo, float hi) { unsigned r; asm volatile("v_cvt_pk_bf16_f32 %0, %1, %2" : "=v"(r) : "v"(lo), "v"(hi)); return r; }
; __device__ __forceinline__ float lo_f(unsigned w) { return __uint_as_float(w << 16); }
; __device__ __forceinline__ float hi_f(unsigned w) { return __uint_as_float(w & 0xffff0000u); }
; #define PG8_BAR __builtin_amdgcn_s_barrier()
;     __device__ __forceinline__ void operator()(f32x4 (&acc)[2][2][4][2], const Unit& u, int wr, int wc, int fr, int fq) const {
;     ...
;         for (int ai = 0; ai < 2; ++ai)
; #pragma unroll
;             for (int m = 0; m < 4; ++m) { const size_t ro = (size_t)(row0 + ai * HALF + m * 16) * DM + col0;
; #pragma unroll
;                 for (int bj = 0; bj < 2; ++bj) { f32x4 x0, x1;
;                     if (Xf32 != nullptr) { x0 = *(const f32x4*)(Xf32 + ro + bj * HALF); x1 = *(const f32x4*)(Xf32 + ro + bj * HALF + 4); }
;                     else { const u32x4 xb = *(const u32x4*)(X + ro + bj * HALF);
;                         x0 = (f32x4){lo_f(xb.x), hi_f(xb.x), lo_f(xb.y), hi_f(xb.y)}; x1 = (f32x4){lo_f(xb.z), hi_f(xb.z), lo_f(xb.w), hi_f(xb.w)}; }
;                     x0 += gv[bj][0] * acc[ai][bj][m][0]; x1 += gv[bj][1] * acc[ai][bj][m][1];
;                     u32x4 w; w.x = cvt_pk_bf16(x0[0], x0[1]); w.y = cvt_pk_bf16(x0[2], x0[3]); w.z = cvt_pk_bf16(x1[0], x1[1]); w.w = cvt_pk_bf16(x1[2], x1[3]);
;                     *(u32x4*)(X + ro + bj * HALF) = w; } }
; template <class Epi, bool ALIGN_EPI = PG8_ALIGN, bool SP2 = PG8_SP2>
; __device__ __forceinline__ void gemm_phase(LAS unsigned char* lds, const int tid, const int K, const Order& S, const Epi& E) {
;     ...
;         cur = nxt; cA = nA; cB = nB; ++ui;
;         if constexpr (ALIGN_EPI) { if (wr == 1) PG8_BAR; }
	s_nop 0
	v_lshlrev_b32_e32 v44, 16, v52
	v_and_b32_e32 v45, 0xffff0000, v52
	v_lshlrev_b32_e32 v46, 16, v53
	v_and_b32_e32 v47, 0xffff0000, v53
	v_lshlrev_b32_e32 v52, 16, v54
	v_and_b32_e32 v53, 0xffff0000, v54
	v_lshlrev_b32_e32 v54, 16, v55
	v_and_b32_e32 v55, 0xffff0000, v55
	v_pk_fma_f32 v[46:47], v[50:51], v[134:135], v[46:47]
	v_pk_fma_f32 v[44:45], v[48:49], v[132:133], v[44:45]
	v_pk_fma_f32 v[48:49], v[42:43], v[130:131], v[54:55]
	v_pk_fma_f32 v[42:43], v[40:41], v[128:129], v[52:53]
	v_cvt_pk_bf16_f32 v40, v44, v45
	v_cvt_pk_bf16_f32 v41, v46, v47
	s_nop 0
	v_cvt_pk_bf16_f32 v42, v42, v43
	v_cvt_pk_bf16_f32 v43, v48, v49
	global_load_dwordx4 v[44:47], v[56:57], off offset:256
	v_add_co_u32_e32 v48, vcc, s68, v158
	global_store_dwordx4 v[64:65], v[40:43], off
	s_nop 0
	v_addc_co_u32_e32 v49, vcc, 0, v159, vcc
	s_waitcnt vmcnt(1)
	v_lshlrev_b32_e32 v40, 16, v44
	v_and_b32_e32 v41, 0xffff0000, v44
	v_lshlrev_b32_e32 v42, 16, v45
	v_and_b32_e32 v43, 0xffff0000, v45
	v_lshlrev_b32_e32 v44, 16, v46
	v_and_b32_e32 v45, 0xffff0000, v46
	v_lshlrev_b32_e32 v46, 16, v47
	v_and_b32_e32 v47, 0xffff0000, v47
	v_pk_fma_f32 v[38:39], v[38:39], v[126:127], v[42:43]
	v_pk_fma_f32 v[36:37], v[36:37], v[124:125], v[40:41]
	v_pk_fma_f32 v[40:41], v[30:31], v[122:123], v[46:47]
	v_pk_fma_f32 v[30:31], v[28:29], v[120:121], v[44:45]
	v_cvt_pk_bf16_f32 v28, v36, v37
	v_cvt_pk_bf16_f32 v29, v38, v39
	s_nop 0
	v_cvt_pk_bf16_f32 v30, v30, v31
	v_cvt_pk_bf16_f32 v31, v40, v41
	global_load_dwordx4 v[36:39], v[48:49], off
	v_lshl_add_u64 v[40:41], v[158:159], 0, s[20:21]
	global_store_dwordx4 v[56:57], v[28:31], off offset:256
	s_waitcnt vmcnt(1)
	s_nop 0
	v_lshlrev_b32_e32 v28, 16, v36
	v_and_b32_e32 v29, 0xffff0000, v36
	v_lshlrev_b32_e32 v30, 16, v37
	v_and_b32_e32 v31, 0xffff0000, v37
	v_lshlrev_b32_e32 v36, 16, v38
	v_and_b32_e32 v37, 0xffff0000, v38
	v_lshlrev_b32_e32 v38, 16, v39
	v_and_b32_e32 v39, 0xffff0000, v39
	v_pk_fma_f32 v[30:31], v[34:35], v[134:135], v[30:31]
	v_pk_fma_f32 v[28:29], v[32:33], v[132:133], v[28:29]
	v_pk_fma_f32 v[32:33], v[26:27], v[130:131], v[38:39]
	v_pk_fma_f32 v[26:27], v[24:25], v[128:129], v[36:37]
	v_cvt_pk_bf16_f32 v24, v28, v29
	v_cvt_pk_bf16_f32 v25, v30, v31
	s_nop 0
	v_cvt_pk_bf16_f32 v26, v26, v27
	v_cvt_pk_bf16_f32 v27, v32, v33
	global_load_dwordx4 v[28:31], v[40:41], off offset:256
	v_add_co_u32_e32 v32, vcc, s69, v158
	global_store_dwordx4 v[48:49], v[24:27], off
	s_nop 0
	v_addc_co_u32_e32 v33, vcc, 0, v159, vcc
	s_andn2_b64 vcc, exec, s[30:31]
	s_mov_b64 s[30:31], -1
	s_waitcnt vmcnt(1)
	v_lshlrev_b32_e32 v24, 16, v28
	v_and_b32_e32 v25, 0xffff0000, v28
	v_lshlrev_b32_e32 v26, 16, v29
	v_and_b32_e32 v27, 0xffff0000, v29
	v_lshlrev_b32_e32 v28, 16, v30
	v_and_b32_e32 v29, 0xffff0000, v30
	v_lshlrev_b32_e32 v30, 16, v31
	v_and_b32_e32 v31, 0xffff0000, v31
	v_pk_fma_f32 v[22:23], v[22:23], v[126:127], v[26:27]
	v_pk_fma_f32 v[20:21], v[20:21], v[124:125], v[24:25]
	v_pk_fma_f32 v[24:25], v[14:15], v[122:123], v[30:31]
	v_pk_fma_f32 v[14:15], v[12:13], v[120:121], v[28:29]
	v_cvt_pk_bf16_f32 v12, v20, v21
	v_cvt_pk_bf16_f32 v13, v22, v23
	s_nop 0
	v_cvt_pk_bf16_f32 v14, v14, v15
	v_cvt_pk_bf16_f32 v15, v24, v25
	global_load_dwordx4 v[20:23], v[32:33], off
	v_lshl_add_u64 v[24:25], v[158:159], 0, s[22:23]
	global_store_dwordx4 v[40:41], v[12:15], off offset:256
	s_waitcnt vmcnt(1)
	s_nop 0
	v_lshlrev_b32_e32 v12, 16, v20
	v_and_b32_e32 v13, 0xffff0000, v20
	v_lshlrev_b32_e32 v14, 16, v21
	v_and_b32_e32 v15, 0xffff0000, v21
	v_lshlrev_b32_e32 v20, 16, v22
	v_and_b32_e32 v21, 0xffff0000, v22
	v_lshlrev_b32_e32 v22, 16, v23
	v_and_b32_e32 v23, 0xffff0000, v23
	v_pk_fma_f32 v[14:15], v[18:19], v[134:135], v[14:15]
	v_pk_fma_f32 v[12:13], v[16:17], v[132:133], v[12:13]
	v_pk_fma_f32 v[16:17], v[10:11], v[130:131], v[22:23]
	v_pk_fma_f32 v[10:11], v[8:9], v[128:129], v[20:21]
	v_cvt_pk_bf16_f32 v8, v12, v13
	v_cvt_pk_bf16_f32 v9, v14, v15
	s_nop 0
	v_cvt_pk_bf16_f32 v10, v10, v11
	v_cvt_pk_bf16_f32 v11, v16, v17
	global_load_dwordx4 v[12:15], v[24:25], off offset:256
	s_nop 0
	global_store_dwordx4 v[32:33], v[8:11], off
	s_waitcnt vmcnt(1)
	s_nop 0
	v_lshlrev_b32_e32 v8, 16, v12
	v_and_b32_e32 v9, 0xffff0000, v12
	v_lshlrev_b32_e32 v10, 16, v13
	v_and_b32_e32 v11, 0xffff0000, v13
	v_lshlrev_b32_e32 v12, 16, v14
	v_and_b32_e32 v13, 0xffff0000, v14
	v_lshlrev_b32_e32 v14, 16, v15
	v_and_b32_e32 v15, 0xffff0000, v15
	v_pk_fma_f32 v[4:5], v[4:5], v[124:125], v[8:9]
	v_pk_fma_f32 v[8:9], v[2:3], v[122:123], v[14:15]
	v_pk_fma_f32 v[2:3], v[0:1], v[120:121], v[12:13]
	v_pk_fma_f32 v[6:7], v[6:7], v[126:127], v[10:11]
	v_cvt_pk_bf16_f32 v0, v4, v5
	s_nop 0
	v_cvt_pk_bf16_f32 v1, v6, v7
	v_cvt_pk_bf16_f32 v2, v2, v3
	v_cvt_pk_bf16_f32 v3, v8, v9
	global_store_dwordx4 v[24:25], v[0:3], off offset:256
	s_cbranch_vccnz .LBB0_1680
	s_andn2_b64 vcc, exec, s[6:7]
	s_cbranch_vccnz .LBB0_1679
	s_barrier
	s_branch .LBB0_1679

; __device__ __forceinline__ unsigned cvt_pk_bf16(float lo, float hi) { unsigned r; asm volatile("v_cvt_pk_bf16_f32 %0, %1, %2" : "=v"(r) : "v"(lo), "v"(hi)); return r; }
; __device__ __forceinline__ float lo_f(unsigned w) { return __uint_as_float(w << 16); }
; __device__ __forceinline__ float hi_f(unsigned w) { return __uint_as_float(w & 0xffff0000u); }
;     __device__ __forceinline__ void operator()(f32x4 (&acc)[2][2][4][2], const Unit& u, int wr, int wc, int fr, int fq) const {
;         const int row0 = u.pm * BM + wr * 64 + fr, col0 = u.pn * BM + wc * 32 + 8 * fq;
;         const int r = u.pm < 32 ? (u.pm >> 3) : 4;
;         const float* gt = mod + (size_t)r * MODW + gate_off + col0;
;         f32x4 gv[2][2];
; #pragma unroll
;         for (int bj = 0; bj < 2; ++bj)
; #pragma unroll
;             for (int n = 0; n < 2; ++n) gv[bj][n] = *(const f32x4*)(gt + bj * HALF + 4 * n);
;         if (u.ks >= 0) {
;             float* pb = PART + ((size_t)u.ks * TC + (size_t)(row0 - TL)) * DM + col0;
; #pragma unroll
;             for (int ai = 0; ai < 2; ++ai)
; #pragma unroll
;                 for (int m = 0; m < 4; ++m)
; #pragma unroll
;                     for (int bj = 0; bj < 2; ++bj) { float* q = pb + (size_t)(ai * HALF + m * 16) * DM + bj * HALF;
;                         *(f32x4*)q = gv[bj][0] * acc[ai][bj][m][0]; *(f32x4*)(q + 4) = gv[bj][1] * acc[ai][bj][m][1]; }
;             return;
;         }
; #pragma unroll
;         for (int ai = 0; ai < 2; ++ai)
; #pragma unroll
;             for (int m = 0; m < 4; ++m) { const size_t ro = (size_t)(row0 + ai * HALF + m * 16) * DM + col0;
; #pragma unroll
;                 for (int bj = 0; bj < 2; ++bj) { f32x4 x0, x1;
;                     if (Xf32 != nullptr) { x0 = *(const f32x4*)(Xf32 + ro + bj * HALF); x1 = *(const f32x4*)(Xf32 + ro + bj * HALF + 4); }
;                     else { const u32x4 xb = *(const u32x4*)(X + ro + bj * HALF);
;                         x0 = (f32x4){lo_f(xb.x), hi_f(xb.x), lo_f(xb.y), hi_f(xb.y)}; x1 = (f32x4){lo_f(xb.z), hi_f(xb.z), lo_f(xb.w), hi_f(xb.w)}; }
;                     x0 += gv[bj][0] * acc[ai][bj][m][0]; x1 += gv[bj][1] * acc[ai][bj][m][1];
;                     u32x4 w; w.x = cvt_pk_bf16(x0[0], x0[1]); w.y = cvt_pk_bf16(x0[2], x0[3]); w.z = cvt_pk_bf16(x1[0], x1[1]); w.w = cvt_pk_bf16(x1[2], x1[3]);
;                     *(u32x4*)(X + ro + bj * HALF) = w; } }
.LBB0_1957:
	v_lshl_add_u32 v160, s69, 8, v164
	s_lshl_b64 s[30:31], s[30:31], 2
	v_lshl_or_b32 v120, s70, 8, v166
	s_add_u32 s30, s2, s30
	v_ashrrev_i32_e32 v161, 31, v160
	v_ashrrev_i32_e32 v121, 31, v120
	v_lshlrev_b64 v[122:123], 12, v[160:161]
	s_addc_u32 s31, s3, s31
	v_lshl_add_u64 v[122:123], s[8:9], 0, v[122:123]
	v_lshlrev_b64 v[162:163], 1, v[120:121]
	v_lshl_add_u64 v[120:121], v[120:121], 2, s[30:31]
	v_lshl_add_u64 v[158:159], v[122:123], 0, v[162:163]
	v_add_co_u32_e32 v122, vcc, s62, v120
	global_load_dwordx4 v[170:173], v[158:159], off
	global_load_dword v244, v[158:159], off
	global_load_dword v244, v[158:159], off offset:256
	v_mov_b32_e32 v240, 0x10000
	v_mov_b32_e32 v241, 0
	v_lshl_add_u64 v[242:243], v[158:159], 0, v[240:241]
	global_load_dword v244, v[242:243], off
	global_load_dword v244, v[242:243], off offset:256
	v_lshl_add_u64 v[242:243], v[242:243], 0, v[240:241]
	global_load_dword v244, v[242:243], off
	global_load_dword v244, v[242:243], off offset:256
	v_lshl_add_u64 v[242:243], v[242:243], 0, v[240:241]
	global_load_dword v244, v[242:243], off
	global_load_dword v244, v[242:243], off offset:256
	v_mov_b32_e32 v240, 0x50000
	v_lshl_add_u64 v[242:243], v[242:243], 0, v[240:241]
	global_load_dword v244, v[242:243], off
	global_load_dword v244, v[242:243], off offset:256
	v_mov_b32_e32 v240, 0x10000
	v_lshl_add_u64 v[242:243], v[242:243], 0, v[240:241]
	global_load_dword v244, v[242:243], off
	global_load_dword v244, v[242:243], off offset:256
	v_lshl_add_u64 v[242:243], v[242:243], 0, v[240:241]
	global_load_dword v244, v[242:243], off
	global_load_dword v244, v[242:243], off offset:256
	v_lshl_add_u64 v[242:243], v[242:243], 0, v[240:241]
	global_load_dword v244, v[242:243], off
	global_load_dword v244, v[242:243], off offset:256
	s_nop 0
	v_addc_co_u32_e32 v123, vcc, 0, v121, vcc
	global_load_dwordx4 v[132:135], v[122:123], off
	v_lshl_add_u64 v[124:125], v[120:121], 0, s[16:17]
	global_load_dwordx4 v[128:131], v[124:125], off offset:16
	global_load_dwordx4 v[120:123], v[124:125], off offset:528
	s_nop 0
	global_load_dwordx4 v[124:127], v[124:125], off offset:512
	s_waitcnt vmcnt(0)
	v_lshlrev_b32_e32 v174, 16, v170
	v_and_b32_e32 v175, 0xffff0000, v170
	v_lshlrev_b32_e32 v170, 16, v171
	v_and_b32_e32 v171, 0xffff0000, v171
	v_lshlrev_b32_e32 v176, 16, v172
	v_and_b32_e32 v177, 0xffff0000, v172
	v_lshlrev_b32_e32 v172, 16, v173
	v_and_b32_e32 v173, 0xffff0000, v173
	v_pk_fma_f32 v[142:143], v[142:143], v[134:135], v[170:171]
	v_pk_fma_f32 v[140:141], v[140:141], v[132:133], v[174:175]
	v_pk_fma_f32 v[170:171], v[138:139], v[130:131], v[172:173]
	v_pk_fma_f32 v[138:139], v[136:137], v[128:129], v[176:177]
	v_cvt_pk_bf16_f32 v136, v140, v141
	v_cvt_pk_bf16_f32 v137, v142, v143
	s_nop 0
	v_cvt_pk_bf16_f32 v138, v138, v139
	v_cvt_pk_bf16_f32 v139, v170, v171
	global_load_dwordx4 v[140:143], v[158:159], off offset:256
	v_or_b32_e32 v170, 16, v160
	v_ashrrev_i32_e32 v171, 31, v170
	v_lshlrev_b64 v[170:171], 12, v[170:171]
	v_lshl_add_u64 v[170:171], s[8:9], 0, v[170:171]
	global_store_dwordx4 v[158:159], v[136:139], off
	v_lshl_add_u64 v[170:171], v[170:171], 0, v[162:163]
	s_waitcnt vmcnt(1)
	v_lshlrev_b32_e32 v136, 16, v140
	v_and_b32_e32 v137, 0xffff0000, v140
	v_lshlrev_b32_e32 v138, 16, v141
	v_and_b32_e32 v139, 0xffff0000, v141
	v_lshlrev_b32_e32 v140, 16, v142
	v_and_b32_e32 v141, 0xffff0000, v142
	v_lshlrev_b32_e32 v142, 16, v143
	v_and_b32_e32 v143, 0xffff0000, v143
	v_pk_fma_f32 v[114:115], v[114:115], v[126:127], v[138:139]
	v_pk_fma_f32 v[112:113], v[112:113], v[124:125], v[136:137]
	v_pk_fma_f32 v[136:137], v[110:111], v[122:123], v[142:143]
	v_pk_fma_f32 v[110:111], v[108:109], v[120:121], v[140:141]
	v_cvt_pk_bf16_f32 v108, v112, v113
	v_cvt_pk_bf16_f32 v109, v114, v115
	s_nop 0
	v_cvt_pk_bf16_f32 v110, v110, v111
	v_cvt_pk_bf16_f32 v111, v136, v137
	global_load_dwordx4 v[112:115], v[170:171], off
	s_nop 0
	global_store_dwordx4 v[158:159], v[108:111], off offset:256
	s_waitcnt vmcnt(1)
	s_nop 0
	v_lshlrev_b32_e32 v108, 16, v112
	v_and_b32_e32 v109, 0xffff0000, v112
	v_lshlrev_b32_e32 v110, 16, v113
	v_and_b32_e32 v111, 0xffff0000, v113
	v_lshlrev_b32_e32 v112, 16, v114
	v_and_b32_e32 v113, 0xffff0000, v114
	v_lshlrev_b32_e32 v114, 16, v115
	v_and_b32_e32 v115, 0xffff0000, v115
	v_pk_fma_f32 v[110:111], v[118:119], v[134:135], v[110:111]
	v_pk_fma_f32 v[108:109], v[116:117], v[132:133], v[108:109]
	v_pk_fma_f32 v[114:115], v[106:107], v[130:131], v[114:115]
	v_pk_fma_f32 v[106:107], v[104:105], v[128:129], v[112:113]
	v_cvt_pk_bf16_f32 v104, v108, v109
	v_cvt_pk_bf16_f32 v105, v110, v111
	v_or_b32_e32 v112, 32, v160
	v_cvt_pk_bf16_f32 v106, v106, v107
	v_cvt_pk_bf16_f32 v107, v114, v115
	global_load_dwordx4 v[108:111], v[170:171], off offset:256
	v_ashrrev_i32_e32 v113, 31, v112
	v_lshlrev_b64 v[112:113], 12, v[112:113]
	v_lshl_add_u64 v[112:113], s[8:9], 0, v[112:113]
	global_store_dwordx4 v[170:171], v[104:107], off
	v_lshl_add_u64 v[112:113], v[112:113], 0, v[162:163]
	s_waitcnt vmcnt(1)
	v_lshlrev_b32_e32 v104, 16, v108
	v_and_b32_e32 v105, 0xffff0000, v108
	v_lshlrev_b32_e32 v106, 16, v109
	v_and_b32_e32 v107, 0xffff0000, v109
	v_lshlrev_b32_e32 v108, 16, v110
	v_and_b32_e32 v109, 0xffff0000, v110
	v_lshlrev_b32_e32 v110, 16, v111
	v_and_b32_e32 v111, 0xffff0000, v111
	v_pk_fma_f32 v[98:99], v[98:99], v[126:127], v[106:107]
	v_pk_fma_f32 v[96:97], v[96:97], v[124:125], v[104:105]
	v_pk_fma_f32 v[104:105], v[94:95], v[122:123], v[110:111]
	v_pk_fma_f32 v[94:95], v[92:93], v[120:121], v[108:109]
	v_cvt_pk_bf16_f32 v92, v96, v97
	v_cvt_pk_bf16_f32 v93, v98, v99
	s_nop 0
	v_cvt_pk_bf16_f32 v94, v94, v95
	v_cvt_pk_bf16_f32 v95, v104, v105
	global_load_dwordx4 v[96:99], v[112:113], off
	s_nop 0
	global_store_dwordx4 v[170:171], v[92:95], off offset:256
	s_waitcnt vmcnt(1)
; __device__ __forceinline__ unsigned cvt_pk_bf16(float lo, float hi) { unsigned r; asm volatile("v_cvt_pk_bf16_f32 %0, %1, %2" : "=v"(r) : "v"(lo), "v"(hi)); return r; }
; __device__ __forceinline__ float lo_f(unsigned w) { return __uint_as_float(w << 16); }
; __device__ __forceinline__ float hi_f(unsigned w) { return __uint_as_float(w & 0xffff0000u); }
;     __device__ __forceinline__ void operator()(f32x4 (&acc)[2][2][4][2], const Unit& u, int wr, int wc, int fr, int fq) const {
;     ...
;         for (int ai = 0; ai < 2; ++ai)
; #pragma unroll
;             for (int m = 0; m < 4; ++m) { const size_t ro = (size_t)(row0 + ai * HALF + m * 16) * DM + col0;
; #pragma unroll
;                 for (int bj = 0; bj < 2; ++bj) { f32x4 x0, x1;
;                     if (Xf32 != nullptr) { x0 = *(const f32x4*)(Xf32 + ro + bj * HALF); x1 = *(const f32x4*)(Xf32 + ro + bj * HALF + 4); }
;                     else { const u32x4 xb = *(const u32x4*)(X + ro + bj * HALF);
;                         x0 = (f32x4){lo_f(xb.x), hi_f(xb.x), lo_f(xb.y), hi_f(xb.y)}; x1 = (f32x4){lo_f(xb.z), hi_f(xb.z), lo_f(xb.w), hi_f(xb.w)}; }
;                     x0 += gv[bj][0] * acc[ai][bj][m][0]; x1 += gv[bj][1] * acc[ai][bj][m][1];
;                     u32x4 w; w.x = cvt_pk_bf16(x0[0], x0[1]); w.y = cvt_pk_bf16(x0[2], x0[3]); w.z = cvt_pk_bf16(x1[0], x1[1]); w.w = cvt_pk_bf16(x1[2], x1[3]);
;                     *(u32x4*)(X + ro + bj * HALF) = w; } }
	s_nop 0
	v_lshlrev_b32_e32 v92, 16, v96
	v_and_b32_e32 v93, 0xffff0000, v96
	v_lshlrev_b32_e32 v94, 16, v97
	v_and_b32_e32 v95, 0xffff0000, v97
	v_lshlrev_b32_e32 v96, 16, v98
	v_and_b32_e32 v97, 0xffff0000, v98
	v_lshlrev_b32_e32 v98, 16, v99
	v_and_b32_e32 v99, 0xffff0000, v99
	v_pk_fma_f32 v[94:95], v[102:103], v[134:135], v[94:95]
	v_pk_fma_f32 v[92:93], v[100:101], v[132:133], v[92:93]
	v_pk_fma_f32 v[98:99], v[90:91], v[130:131], v[98:99]
	v_pk_fma_f32 v[90:91], v[88:89], v[128:129], v[96:97]
	v_cvt_pk_bf16_f32 v88, v92, v93
	v_cvt_pk_bf16_f32 v89, v94, v95
	v_or_b32_e32 v96, 48, v160
	v_cvt_pk_bf16_f32 v90, v90, v91
	v_cvt_pk_bf16_f32 v91, v98, v99
	global_load_dwordx4 v[92:95], v[112:113], off offset:256
	v_ashrrev_i32_e32 v97, 31, v96
	v_lshlrev_b64 v[96:97], 12, v[96:97]
	v_lshl_add_u64 v[96:97], s[8:9], 0, v[96:97]
	global_store_dwordx4 v[112:113], v[88:91], off
	v_lshl_add_u64 v[96:97], v[96:97], 0, v[162:163]
	s_waitcnt vmcnt(1)
	v_lshlrev_b32_e32 v88, 16, v92
	v_and_b32_e32 v89, 0xffff0000, v92
	v_lshlrev_b32_e32 v90, 16, v93
	v_and_b32_e32 v91, 0xffff0000, v93
	v_lshlrev_b32_e32 v92, 16, v94
	v_and_b32_e32 v93, 0xffff0000, v94
	v_lshlrev_b32_e32 v94, 16, v95
	v_and_b32_e32 v95, 0xffff0000, v95
	v_pk_fma_f32 v[82:83], v[82:83], v[126:127], v[90:91]
	v_pk_fma_f32 v[80:81], v[80:81], v[124:125], v[88:89]
	v_pk_fma_f32 v[88:89], v[78:79], v[122:123], v[94:95]
	v_pk_fma_f32 v[78:79], v[76:77], v[120:121], v[92:93]
	v_cvt_pk_bf16_f32 v76, v80, v81
	v_cvt_pk_bf16_f32 v77, v82, v83
	s_nop 0
	v_cvt_pk_bf16_f32 v78, v78, v79
	v_cvt_pk_bf16_f32 v79, v88, v89
	global_load_dwordx4 v[80:83], v[96:97], off
	s_nop 0
	global_store_dwordx4 v[112:113], v[76:79], off offset:256
	s_waitcnt vmcnt(1)
	s_nop 0
	v_lshlrev_b32_e32 v76, 16, v80
	v_and_b32_e32 v77, 0xffff0000, v80
	v_lshlrev_b32_e32 v78, 16, v81
	v_and_b32_e32 v79, 0xffff0000, v81
	v_lshlrev_b32_e32 v80, 16, v82
	v_and_b32_e32 v81, 0xffff0000, v82
	v_lshlrev_b32_e32 v82, 16, v83
	v_and_b32_e32 v83, 0xffff0000, v83
	v_pk_fma_f32 v[78:79], v[86:87], v[134:135], v[78:79]
	v_pk_fma_f32 v[76:77], v[84:85], v[132:133], v[76:77]
	v_pk_fma_f32 v[82:83], v[74:75], v[130:131], v[82:83]
	v_pk_fma_f32 v[74:75], v[72:73], v[128:129], v[80:81]
	v_cvt_pk_bf16_f32 v72, v76, v77
	v_cvt_pk_bf16_f32 v73, v78, v79
	v_add_co_u32_e32 v80, vcc, s63, v158
	v_cvt_pk_bf16_f32 v74, v74, v75
	v_cvt_pk_bf16_f32 v75, v82, v83
	global_load_dwordx4 v[76:79], v[96:97], off offset:256
	s_nop 0
	v_addc_co_u32_e32 v81, vcc, 0, v159, vcc
	global_store_dwordx4 v[96:97], v[72:75], off
	s_waitcnt vmcnt(1)
	s_nop 0
	v_lshlrev_b32_e32 v72, 16, v76
	v_and_b32_e32 v73, 0xffff0000, v76
	v_lshlrev_b32_e32 v74, 16, v77
	v_and_b32_e32 v75, 0xffff0000, v77
	v_lshlrev_b32_e32 v76, 16, v78
	v_and_b32_e32 v77, 0xffff0000, v78
	v_lshlrev_b32_e32 v78, 16, v79
	v_and_b32_e32 v79, 0xffff0000, v79
	v_pk_fma_f32 v[70:71], v[70:71], v[126:127], v[74:75]
	v_pk_fma_f32 v[68:69], v[68:69], v[124:125], v[72:73]
	v_pk_fma_f32 v[72:73], v[66:67], v[122:123], v[78:79]
	v_pk_fma_f32 v[66:67], v[64:65], v[120:121], v[76:77]
	v_cvt_pk_bf16_f32 v64, v68, v69
	v_cvt_pk_bf16_f32 v65, v70, v71
	s_nop 0
	v_cvt_pk_bf16_f32 v66, v66, v67
	v_cvt_pk_bf16_f32 v67, v72, v73
	global_load_dwordx4 v[68:71], v[80:81], off
	v_lshl_add_u64 v[72:73], v[158:159], 0, s[18:19]
	global_store_dwordx4 v[96:97], v[64:67], off offset:256
	s_waitcnt vmcnt(1)
	s_nop 0
	v_lshlrev_b32_e32 v64, 16, v68
	v_and_b32_e32 v65, 0xffff0000, v68
	v_lshlrev_b32_e32 v66, 16, v69
	v_and_b32_e32 v67, 0xffff0000, v69
	v_lshlrev_b32_e32 v68, 16, v70
	v_and_b32_e32 v69, 0xffff0000, v70
	v_lshlrev_b32_e32 v70, 16, v71
	v_and_b32_e32 v71, 0xffff0000, v71
	v_pk_fma_f32 v[62:63], v[62:63], v[134:135], v[66:67]
	v_pk_fma_f32 v[60:61], v[60:61], v[132:133], v[64:65]
	v_pk_fma_f32 v[64:65], v[58:59], v[130:131], v[70:71]
	v_pk_fma_f32 v[58:59], v[56:57], v[128:129], v[68:69]
	v_cvt_pk_bf16_f32 v56, v60, v61
	v_cvt_pk_bf16_f32 v57, v62, v63
	s_nop 0
	v_cvt_pk_bf16_f32 v58, v58, v59
	v_cvt_pk_bf16_f32 v59, v64, v65
	global_load_dwordx4 v[60:63], v[72:73], off offset:256
	v_add_co_u32_e32 v64, vcc, s64, v158
	global_store_dwordx4 v[80:81], v[56:59], off
	s_nop 0
	v_addc_co_u32_e32 v65, vcc, 0, v159, vcc
	s_waitcnt vmcnt(1)
	v_lshlrev_b32_e32 v56, 16, v60
	v_and_b32_e32 v57, 0xffff0000, v60
	v_lshlrev_b32_e32 v58, 16, v61
	v_and_b32_e32 v59, 0xffff0000, v61
	v_lshlrev_b32_e32 v60, 16, v62
	v_and_b32_e32 v61, 0xffff0000, v62
	v_lshlrev_b32_e32 v62, 16, v63
	v_and_b32_e32 v63, 0xffff0000, v63
	v_pk_fma_f32 v[54:55], v[54:55], v[126:127], v[58:59]
	v_pk_fma_f32 v[52:53], v[52:53], v[124:125], v[56:57]
	v_pk_fma_f32 v[56:57], v[46:47], v[122:123], v[62:63]
	v_pk_fma_f32 v[46:47], v[44:45], v[120:121], v[60:61]
	v_cvt_pk_bf16_f32 v44, v52, v53
	v_cvt_pk_bf16_f32 v45, v54, v55
	s_nop 0
	v_cvt_pk_bf16_f32 v46, v46, v47
	v_cvt_pk_bf16_f32 v47, v56, v57
	global_load_dwordx4 v[52:55], v[64:65], off
	v_lshl_add_u64 v[56:57], v[158:159], 0, s[20:21]
	global_store_dwordx4 v[72:73], v[44:47], off offset:256
	s_waitcnt vmcnt(1)
; __device__ __forceinline__ unsigned cvt_pk_bf16(float lo, float hi) { unsigned r; asm volatile("v_cvt_pk_bf16_f32 %0, %1, %2" : "=v"(r) : "v"(lo), "v"(hi)); return r; }
; __device__ __forceinline__ float lo_f(unsigned w) { return __uint_as_float(w << 16); }
; __device__ __forceinline__ float hi_f(unsigned w) { return __uint_as_float(w & 0xffff0000u); }
; #define PG8_BAR __builtin_amdgcn_s_barrier()
;     __device__ __forceinline__ void operator()(f32x4 (&acc)[2][2][4][2], const Unit& u, int wr, int wc, int fr, int fq) const {
;     ...
;         for (int ai = 0; ai < 2; ++ai)
; #pragma unroll
;             for (int m = 0; m < 4; ++m) { const size_t ro = (size_t)(row0 + ai * HALF + m * 16) * DM + col0;
; #pragma unroll
;                 for (int bj = 0; bj < 2; ++bj) { f32x4 x0, x1;
;                     if (Xf32 != nullptr) { x0 = *(const f32x4*)(Xf32 + ro + bj * HALF); x1 = *(const f32x4*)(Xf32 + ro + bj * HALF + 4); }
;                     else { const u32x4 xb = *(const u32x4*)(X + ro + bj * HALF);
;                         x0 = (f32x4){lo_f(xb.x), hi_f(xb.x), lo_f(xb.y), hi_f(xb.y)}; x1 = (f32x4){lo_f(xb.z), hi_f(xb.z), lo_f(xb.w), hi_f(xb.w)}; }
;                     x0 += gv[bj][0] * acc[ai][bj][m][0]; x1 += gv[bj][1] * acc[ai][bj][m][1];
;                     u32x4 w; w.x = cvt_pk_bf16(x0[0], x0[1]); w.y = cvt_pk_bf16(x0[2], x0[3]); w.z = cvt_pk_bf16(x1[0], x1[1]); w.w = cvt_pk_bf16(x1[2], x1[3]);
;                     *(u32x4*)(X + ro + bj * HALF) = w; } }
; template <class Epi, bool ALIGN_EPI = PG8_ALIGN, bool SP2 = PG8_SP2>
; __device__ __forceinline__ void gemm_phase(LAS unsigned char* lds, const int tid, const int K, const Order& S, const Epi& E) {
;     ...
;         cur = nxt; cA = nA; cB = nB; ++ui;
;         if constexpr (ALIGN_EPI) { if (wr == 1) PG8_BAR; }
	s_nop 0
	v_lshlrev_b32_e32 v44, 16, v52
	v_and_b32_e32 v45, 0xffff0000, v52
	v_lshlrev_b32_e32 v46, 16, v53
	v_and_b32_e32 v47, 0xffff0000, v53
	v_lshlrev_b32_e32 v52, 16, v54
	v_and_b32_e32 v53, 0xffff0000, v54
	v_lshlrev_b32_e32 v54, 16, v55
	v_and_b32_e32 v55, 0xffff0000, v55
	v_pk_fma_f32 v[46:47], v[50:51], v[134:135], v[46:47]
	v_pk_fma_f32 v[44:45], v[48:49], v[132:133], v[44:45]
	v_pk_fma_f32 v[48:49], v[42:43], v[130:131], v[54:55]
	v_pk_fma_f32 v[42:43], v[40:41], v[128:129], v[52:53]
	v_cvt_pk_bf16_f32 v40, v44, v45
	v_cvt_pk_bf16_f32 v41, v46, v47
	s_nop 0
	v_cvt_pk_bf16_f32 v42, v42, v43
	v_cvt_pk_bf16_f32 v43, v48, v49
	global_load_dwordx4 v[44:47], v[56:57], off offset:256
	v_add_co_u32_e32 v48, vcc, s65, v158
	global_store_dwordx4 v[64:65], v[40:43], off
	s_nop 0
	v_addc_co_u32_e32 v49, vcc, 0, v159, vcc
	s_waitcnt vmcnt(1)
	v_lshlrev_b32_e32 v40, 16, v44
	v_and_b32_e32 v41, 0xffff0000, v44
	v_lshlrev_b32_e32 v42, 16, v45
	v_and_b32_e32 v43, 0xffff0000, v45
	v_lshlrev_b32_e32 v44, 16, v46
	v_and_b32_e32 v45, 0xffff0000, v46
	v_lshlrev_b32_e32 v46, 16, v47
	v_and_b32_e32 v47, 0xffff0000, v47
	v_pk_fma_f32 v[38:39], v[38:39], v[126:127], v[42:43]
	v_pk_fma_f32 v[36:37], v[36:37], v[124:125], v[40:41]
	v_pk_fma_f32 v[40:41], v[30:31], v[122:123], v[46:47]
	v_pk_fma_f32 v[30:31], v[28:29], v[120:121], v[44:45]
	v_cvt_pk_bf16_f32 v28, v36, v37
	v_cvt_pk_bf16_f32 v29, v38, v39
	s_nop 0
	v_cvt_pk_bf16_f32 v30, v30, v31
	v_cvt_pk_bf16_f32 v31, v40, v41
	global_load_dwordx4 v[36:39], v[48:49], off
	v_lshl_add_u64 v[40:41], v[158:159], 0, s[22:23]
	global_store_dwordx4 v[56:57], v[28:31], off offset:256
	s_waitcnt vmcnt(1)
	s_nop 0
	v_lshlrev_b32_e32 v28, 16, v36
	v_and_b32_e32 v29, 0xffff0000, v36
	v_lshlrev_b32_e32 v30, 16, v37
	v_and_b32_e32 v31, 0xffff0000, v37
	v_lshlrev_b32_e32 v36, 16, v38
	v_and_b32_e32 v37, 0xffff0000, v38
	v_lshlrev_b32_e32 v38, 16, v39
	v_and_b32_e32 v39, 0xffff0000, v39
	v_pk_fma_f32 v[30:31], v[34:35], v[134:135], v[30:31]
	v_pk_fma_f32 v[28:29], v[32:33], v[132:133], v[28:29]
	v_pk_fma_f32 v[32:33], v[26:27], v[130:131], v[38:39]
	v_pk_fma_f32 v[26:27], v[24:25], v[128:129], v[36:37]
	v_cvt_pk_bf16_f32 v24, v28, v29
	v_cvt_pk_bf16_f32 v25, v30, v31
	s_nop 0
	v_cvt_pk_bf16_f32 v26, v26, v27
	v_cvt_pk_bf16_f32 v27, v32, v33
	global_load_dwordx4 v[28:31], v[40:41], off offset:256
	v_add_co_u32_e32 v32, vcc, s66, v158
	global_store_dwordx4 v[48:49], v[24:27], off
	s_nop 0
	v_addc_co_u32_e32 v33, vcc, 0, v159, vcc
	s_and_b64 vcc, exec, s[4:5]
	s_mov_b64 s[4:5], -1
	s_waitcnt vmcnt(1)
	v_lshlrev_b32_e32 v24, 16, v28
	v_and_b32_e32 v25, 0xffff0000, v28
	v_lshlrev_b32_e32 v26, 16, v29
	v_and_b32_e32 v27, 0xffff0000, v29
	v_lshlrev_b32_e32 v28, 16, v30
	v_and_b32_e32 v29, 0xffff0000, v30
	v_lshlrev_b32_e32 v30, 16, v31
	v_and_b32_e32 v31, 0xffff0000, v31
	v_pk_fma_f32 v[22:23], v[22:23], v[126:127], v[26:27]
	v_pk_fma_f32 v[20:21], v[20:21], v[124:125], v[24:25]
	v_pk_fma_f32 v[24:25], v[14:15], v[122:123], v[30:31]
	v_pk_fma_f32 v[14:15], v[12:13], v[120:121], v[28:29]
	v_cvt_pk_bf16_f32 v12, v20, v21
	v_cvt_pk_bf16_f32 v13, v22, v23
	s_nop 0
	v_cvt_pk_bf16_f32 v14, v14, v15
	v_cvt_pk_bf16_f32 v15, v24, v25
	global_load_dwordx4 v[20:23], v[32:33], off
	v_lshl_add_u64 v[24:25], v[158:159], 0, s[24:25]
	global_store_dwordx4 v[40:41], v[12:15], off offset:256
	s_waitcnt vmcnt(1)
	s_nop 0
	v_lshlrev_b32_e32 v12, 16, v20
	v_and_b32_e32 v13, 0xffff0000, v20
	v_lshlrev_b32_e32 v14, 16, v21
	v_and_b32_e32 v15, 0xffff0000, v21
	v_lshlrev_b32_e32 v20, 16, v22
	v_and_b32_e32 v21, 0xffff0000, v22
	v_lshlrev_b32_e32 v22, 16, v23
	v_and_b32_e32 v23, 0xffff0000, v23
	v_pk_fma_f32 v[14:15], v[18:19], v[134:135], v[14:15]
	v_pk_fma_f32 v[12:13], v[16:17], v[132:133], v[12:13]
	v_pk_fma_f32 v[16:17], v[10:11], v[130:131], v[22:23]
	v_pk_fma_f32 v[10:11], v[8:9], v[128:129], v[20:21]
	v_cvt_pk_bf16_f32 v8, v12, v13
	v_cvt_pk_bf16_f32 v9, v14, v15
	s_nop 0
	v_cvt_pk_bf16_f32 v10, v10, v11
	v_cvt_pk_bf16_f32 v11, v16, v17
	global_load_dwordx4 v[12:15], v[24:25], off offset:256
	s_nop 0
	global_store_dwordx4 v[32:33], v[8:11], off
	s_waitcnt vmcnt(1)
	s_nop 0
	v_lshlrev_b32_e32 v8, 16, v12
	v_and_b32_e32 v9, 0xffff0000, v12
	v_lshlrev_b32_e32 v10, 16, v13
	v_and_b32_e32 v11, 0xffff0000, v13
	v_lshlrev_b32_e32 v12, 16, v14
	v_and_b32_e32 v13, 0xffff0000, v14
	v_lshlrev_b32_e32 v14, 16, v15
	v_and_b32_e32 v15, 0xffff0000, v15
	v_pk_fma_f32 v[4:5], v[4:5], v[124:125], v[8:9]
	v_pk_fma_f32 v[8:9], v[2:3], v[122:123], v[14:15]
	v_pk_fma_f32 v[2:3], v[0:1], v[120:121], v[12:13]
	v_pk_fma_f32 v[6:7], v[6:7], v[126:127], v[10:11]
	v_cvt_pk_bf16_f32 v0, v4, v5
	s_nop 0
	v_cvt_pk_bf16_f32 v1, v6, v7
	v_cvt_pk_bf16_f32 v2, v2, v3
	v_cvt_pk_bf16_f32 v3, v8, v9
	global_store_dwordx4 v[24:25], v[0:3], off offset:256
	s_cbranch_vccnz .LBB0_1938
	s_andn2_b64 vcc, exec, s[6:7]
	s_cbranch_vccnz .LBB0_1937
	s_barrier
	s_branch .LBB0_1937
